# SGPR-base LDS-DMA addressing also in the out-proj and down-proj GEMM loops (5 of 8 loop instances converted)
# speedup vs baseline: 1.0115x; 1.0020x over previous
; #define PG8_STAGE(bufoff, gbase, RR, ld) do { _Pragma("unroll") for (int _i = 0; _i < 2; ++_i) \
;         __builtin_amdgcn_global_load_lds((const unsigned*)((const char*)(gbase) + (RR)[_i] * (ld) + C2[_i]), (LAS unsigned*)(lds + (bufoff) + ldsw + _i * 8192), 16, 0, 0); } while (0)
; #define PG8_WAIT_V(n) asm volatile("s_waitcnt vmcnt(" #n ")" ::: "memory")
; #define PG8_BAR __builtin_amdgcn_s_barrier()
; template <class Sched, class Epi>
; __device__ __forceinline__ void gemm_run(LAS unsigned char* lds, const Sched& S, const Epi& E) {
;     const int tid = threadIdx.x, wid = __builtin_amdgcn_readfirstlane(tid >> 6), lane = tid & 63, wr = wid >> 2, wc = wid & 3, fr = lane & 15, fq = lane >> 4;
;     unsigned RA[2], RB[2], C2[2];
; #pragma unroll
;     for (int i = 0; i < 2; ++i) { int R, C; stage_rc(tid * 16 + i * 8192, R, C); RA[i] = (unsigned)R; RB[i] = (unsigned)((R & ~31) + perm32(R & 31)); C2[i] = (unsigned)(C * 2); }
;     const unsigned ldsw = (unsigned)wid * 1024u;
;     const int aoff = lds_byte(wr * 64 + fr, fq * 8), boff = lds_byte(wc * 32 + fr, fq * 8);
;     ...
;     Unit cur, nxt; int ui = 0;
;     if (!S.next(0, cur)) return;
;     f32x4 acc[2][2][4][2];
; #pragma unroll
;     for (int a = 0; a < 2; ++a)
; #pragma unroll
;         for (int b = 0; b < 2; ++b)
; #pragma unroll
;             for (int m = 0; m < 4; ++m)
; #pragma unroll
;                 for (int n = 0; n < 2; ++n) acc[a][b][m][n] = (f32x4){0.f, 0.f, 0.f, 0.f};
;     bf16x8 At[4][2], B0[2][2], B1[2][2];
;     const char* cA = cur.A; const char* cB = cur.B; unsigned lda = cur.lda, ldb = cur.ldb;
;     constexpr unsigned kstep = BK * 2;
;     PG8_STAGE(PG8_SB(0, 0), cB, RB, ldb); PG8_STAGE(PG8_SB(0, 1), cB + (size_t)HALF * ldb, RB, ldb); PG8_STAGE(PG8_SA(0, 0), cA, RA, lda); PG8_STAGE(PG8_SA(0, 1), cA + (size_t)HALF * lda, RA, lda);
;     if (wr == 1) PG8_BAR;
;     PG8_WAIT_V(2); PG8_BAR;
;     PG8_STAGE(PG8_SB(1, 0), cB + kstep, RB, ldb); PG8_STAGE(PG8_SA(1, 0), cA + kstep, RA, lda); PG8_STAGE(PG8_SB(1, 1), cB + (size_t)HALF * ldb + kstep, RB, ldb);
;     PG8_WAIT_V(6); PG8_BAR;
.LBB0_888:
	s_lshl_b32 s1, s1, 5
	s_mov_b64 s[10:11], 0x80
	s_and_b32 s1, s1, 0x60
	s_add_i32 m0, s33, 0x18000
	v_lshl_add_u64 v[2:3], v[2:3], 0, s[10:11]
	s_lshl_b32 s13, s0, 13
	s_lshl_b32 s16, s1, 7
	s_waitcnt vmcnt(2)
	s_barrier
	global_load_lds_dwordx4 v[2:3], off
	v_lshl_add_u64 v[2:3], v[4:5], 0, s[10:11]
	s_add_i32 m0, s33, 0x1a000
	s_add_i32 s55, s33, 0x8000
	s_add_i32 s56, s33, 0xa000
	global_load_lds_dwordx4 v[2:3], off
	v_lshl_add_u64 v[2:3], v[6:7], 0, s[10:11]
	s_mov_b32 m0, s55
	s_add_u32 s14, s38, 0x80080
	global_load_lds_dwordx4 v[2:3], off
	v_lshl_add_u64 v[2:3], v[8:9], 0, s[10:11]
	s_mov_b32 m0, s56
	s_addc_u32 s15, s39, 0
	global_load_lds_dwordx4 v[2:3], off
	v_lshl_add_u64 v[2:3], s[14:15], 0, v[156:157]
	s_add_i32 m0, s33, 0x1c000
	v_lshl_add_u64 v[2:3], v[2:3], 0, v[154:155]
	global_load_lds_dwordx4 v[2:3], off
	v_lshl_add_u64 v[2:3], s[14:15], 0, v[160:161]
	v_lshl_add_u64 v[2:3], v[2:3], 0, v[154:155]
	s_add_i32 m0, s33, 0x1e000
	v_and_b32_e32 v5, 32, v188
	global_load_lds_dwordx4 v[2:3], off
	v_bfe_u32 v3, v0, 4, 2
	v_and_b32_e32 v2, 15, v0
	v_lshlrev_b32_e32 v4, 4, v3
	v_lshl_or_b32 v189, s0, 6, v2
	v_lshl_or_b32 v2, v2, 6, v4
	v_bitop3_b32 v6, v2, s13, v5 bitop3:0xde
	v_lshlrev_b32_e32 v2, 6, v0
	s_movk_i32 s0, 0x3c0
	s_cmpk_lt_u32 s12, 0x100
	v_and_or_b32 v2, v2, s0, v4
	s_cselect_b64 s[12:13], -1, 0
	s_add_u32 s57, s86, 0x6600000
	v_bitop3_b32 v190, s16, v2, v5 bitop3:0xf6
	v_lshl_or_b32 v2, v3, 3, s1
	s_addc_u32 s58, s87, 0
	s_add_u32 s59, s86, 0xaa00000
	v_lshlrev_b32_e32 v158, 1, v2
	v_cmp_eq_u32_e64 s[0:1], 0, v3
	s_addc_u32 s60, s87, 0
	v_lshl_add_u64 v[4:5], s[86:87], 0, v[158:159]
	s_mov_b64 s[14:15], 0x10300000
	v_lshlrev_b32_e32 v3, 9, v0
	v_lshl_add_u64 v[166:167], v[4:5], 0, s[14:15]
	s_add_u32 s14, s86, 0x400000
	v_and_b32_e32 v3, 0x30000, v3
	v_lshlrev_b32_e32 v4, 12, v10
	v_add_u32_e32 v5, v11, v12
	s_addc_u32 s15, s87, 0
	v_or3_b32 v158, v3, v4, v5
	v_lshlrev_b32_e32 v3, 5, v13
	s_mov_b64 s[18:19], 0x80080
	s_waitcnt vmcnt(6)
	s_add_u32 s16, s86, 0x30000
	v_and_b32_e32 v3, 0x70000, v3
	s_addc_u32 s17, s87, 0
	v_lshl_add_u64 v[168:169], v[158:159], 0, s[18:19]
	v_or3_b32 v158, v3, v4, v5
	s_add_i32 s61, 0, 0x10000
	s_add_i32 s62, 0, 0x14000
	v_mbcnt_lo_u32_b32 v3, -1, 0
	v_lshl_add_u64 v[170:171], v[158:159], 0, s[18:19]
	v_add_u32_e32 v191, s61, v190
	v_add_u32_e32 v192, s62, v190
	v_add_u32_e32 v193, 0, v6
	v_mbcnt_hi_u32_b32 v194, -1, v3
	v_lshlrev_b32_e32 v158, 1, v2
	s_mov_b64 s[28:29], s[38:39]
	s_mov_b64 s[20:21], s[36:37]
	v_add_u32_e32 v156, v156, v154
	v_add_u32_e32 v160, v160, v154
	v_add_u32_e32 v162, v162, v154
	v_add_u32_e32 v164, v164, v154
	s_barrier
	s_branch .LBB0_891

; #define PG8_STAGE(bufoff, gbase, RR, ld) do { _Pragma("unroll") for (int _i = 0; _i < 2; ++_i) \
;         __builtin_amdgcn_global_load_lds((const unsigned*)((const char*)(gbase) + (RR)[_i] * (ld) + C2[_i]), (LAS unsigned*)(lds + (bufoff) + ldsw + _i * 8192), 16, 0, 0); } while (0)
; #define PG8_LDA(dst, b, h) do { _Pragma("unroll") for (int m = 0; m < 4; ++m) _Pragma("unroll") for (int k = 0; k < 2; ++k) dst[m][k] = *(const LAS bf16x8*)(lds + PG8_SA(b, h) + aoff + m * 2048 + k * 1024); } while (0)
; #define PG8_LDB(dst, b, h) do { _Pragma("unroll") for (int n = 0; n < 2; ++n) _Pragma("unroll") for (int k = 0; k < 2; ++k) dst[n][k] = *(const LAS bf16x8*)(lds + PG8_SB(b, h) + boff + n * 2048 + k * 1024); } while (0)
; #define PG8_WAIT_V(n) asm volatile("s_waitcnt vmcnt(" #n ")" ::: "memory")
; #define PG8_WAIT_L(n) asm volatile("s_waitcnt lgkmcnt(" #n ")" ::: "memory")
; #define PG8_BAR __builtin_amdgcn_s_barrier()
; #define PG8_SCHED __builtin_amdgcn_sched_barrier(0)
; template <class Sched, class Epi>
; __device__ __forceinline__ void gemm_run(LAS unsigned char* lds, const Sched& S, const Epi& E) {
;     ...
;         const bool has_next = S.next(ui + 1, nxt);
;         const char* nA = has_next ? nxt.A : cA; const char* nB = has_next ? nxt.B : cB; const unsigned nlda = has_next ? nxt.lda : lda, nldb = has_next ? nxt.ldb : ldb;
;         const int nt = cur.nt;
;         for (int t = 0; t < nt; t += 2) {
;             const bool last = (t == nt - 2);
;             const char* a1 = cA + (size_t)(t + 1) * kstep;
;             const char* a2 = last ? nA : cA + (size_t)(t + 2) * kstep; const char* b2 = last ? nB : cB + (size_t)(t + 2) * kstep;
;             const unsigned la2 = last ? nlda : lda, lb2 = last ? nldb : ldb;
;             const char* a3 = a2 + kstep; const char* b3 = b2 + kstep;
;             PG8_LDB(B0, 0, 0); PG8_LDB(B1, 0, 1); PG8_SCHED; PG8_LDA(At, 0, 0); PG8_STAGE(PG8_SA(1, 1), a1 + (size_t)HALF * lda, RA, lda);
;             PG8_WAIT_V(8); PG8_WAIT_L(0); PG8_BAR; PG8_MMA(0, 0, At, B0); PG8_MMA(0, 1, At, B1); PG8_BAR; PG8_SCHED;
;             PG8_LDA(At, 0, 1); PG8_STAGE(PG8_SB(0, 0), b2, RB, lb2); PG8_STAGE(PG8_SB(0, 1), b2 + (size_t)HALF * lb2, RB, lb2); PG8_STAGE(PG8_SA(0, 0), a2, RA, la2);
;             PG8_WAIT_V(8); PG8_WAIT_L(0); PG8_BAR; PG8_MMA(1, 0, At, B0); PG8_MMA(1, 1, At, B1); PG8_BAR; PG8_SCHED;
.LBB0_893:
	s_add_u32 s19, s38, 0x100
	s_addc_u32 s31, s39, 0
	s_mov_b32 s44, -2
	s_mov_b64 s[38:39], 0
	s_waitcnt lgkmcnt(0)
	ds_read_b128 v[134:137], v191
	ds_read_b128 v[138:141], v191 offset:1024
	ds_read_b128 v[142:145], v191 offset:2048
	ds_read_b128 v[146:149], v191 offset:3072
	ds_read_b128 v[150:153], v192
	ds_read_b128 v[172:175], v192 offset:1024
	ds_read_b128 v[176:179], v192 offset:2048
	ds_read_b128 v[180:183], v192 offset:3072
	s_add_u32 s40, s36, s38
	s_addc_u32 s41, s37, s39
	s_mov_b32 s98, s40
	s_mov_b32 s99, s41
	s_add_u32 s40, s40, 0x100
	s_addc_u32 s41, s41, 0
	s_add_u32 s45, s19, s38
	s_addc_u32 s46, s31, s39
	s_cmpk_eq_i32 s38, 0xf00
	s_cselect_b32 s43, s21, s41
	s_cselect_b32 s42, s20, s40
	s_cselect_b32 s41, s29, s46
	s_cselect_b32 s40, s28, s45
	s_mov_b64 s[100:101], s[42:43]
	s_add_i32 m0, s33, 0xc000
	ds_read_b128 v[184:187], v193
	ds_read_b128 v[196:199], v193 offset:1024
	ds_read_b128 v[200:203], v193 offset:2048
	ds_read_b128 v[204:207], v193 offset:3072
	ds_read_b128 v[208:211], v193 offset:4096
	ds_read_b128 v[212:215], v193 offset:5120
	ds_read_b128 v[216:219], v193 offset:6144
	ds_read_b128 v[220:223], v193 offset:7168
	global_load_lds_dwordx4 v168, s[98:99]
	s_add_i32 m0, s33, 0xe000
	s_nop 0
	global_load_lds_dwordx4 v170, s[98:99]
	s_waitcnt vmcnt(8)
	s_waitcnt lgkmcnt(0)
	s_barrier
	s_waitcnt lgkmcnt(0)
	v_mfma_f32_16x16x32_bf16 v[126:129], v[134:137], v[184:187], 0
	v_mfma_f32_16x16x32_bf16 v[122:125], v[142:145], v[184:187], 0
	v_mfma_f32_16x16x32_bf16 v[110:113], v[134:137], v[200:203], 0
	v_mfma_f32_16x16x32_bf16 v[106:109], v[142:145], v[200:203], 0
	v_mfma_f32_16x16x32_bf16 v[94:97], v[134:137], v[208:211], 0
	v_mfma_f32_16x16x32_bf16 v[90:93], v[142:145], v[208:211], 0
	v_mfma_f32_16x16x32_bf16 v[78:81], v[134:137], v[216:219], 0
	v_mfma_f32_16x16x32_bf16 v[74:77], v[142:145], v[216:219], 0
	v_mfma_f32_16x16x32_bf16 v[126:129], v[138:141], v[196:199], v[126:129]
	v_mfma_f32_16x16x32_bf16 v[122:125], v[146:149], v[196:199], v[122:125]
	v_mfma_f32_16x16x32_bf16 v[110:113], v[138:141], v[204:207], v[110:113]
	v_mfma_f32_16x16x32_bf16 v[106:109], v[146:149], v[204:207], v[106:109]
	v_mfma_f32_16x16x32_bf16 v[94:97], v[138:141], v[212:215], v[94:97]
	v_mfma_f32_16x16x32_bf16 v[90:93], v[146:149], v[212:215], v[90:93]
	v_mfma_f32_16x16x32_bf16 v[78:81], v[138:141], v[220:223], v[78:81]
	v_mfma_f32_16x16x32_bf16 v[74:77], v[146:149], v[220:223], v[74:77]
	v_mfma_f32_16x16x32_bf16 v[118:121], v[150:153], v[184:187], 0
	v_mfma_f32_16x16x32_bf16 v[114:117], v[176:179], v[184:187], 0
	v_mfma_f32_16x16x32_bf16 v[102:105], v[150:153], v[200:203], 0
	v_mfma_f32_16x16x32_bf16 v[98:101], v[176:179], v[200:203], 0
	v_mfma_f32_16x16x32_bf16 v[86:89], v[150:153], v[208:211], 0
	v_mfma_f32_16x16x32_bf16 v[82:85], v[176:179], v[208:211], 0
	v_mfma_f32_16x16x32_bf16 v[70:73], v[150:153], v[216:219], 0
	v_mfma_f32_16x16x32_bf16 v[66:69], v[176:179], v[216:219], 0
	v_mfma_f32_16x16x32_bf16 v[118:121], v[172:175], v[196:199], v[118:121]
	v_mfma_f32_16x16x32_bf16 v[114:117], v[180:183], v[196:199], v[114:117]
	v_mfma_f32_16x16x32_bf16 v[102:105], v[172:175], v[204:207], v[102:105]
	v_mfma_f32_16x16x32_bf16 v[98:101], v[180:183], v[204:207], v[98:101]
	v_mfma_f32_16x16x32_bf16 v[86:89], v[172:175], v[212:215], v[86:89]
	v_mfma_f32_16x16x32_bf16 v[82:85], v[180:183], v[212:215], v[82:85]
	v_mfma_f32_16x16x32_bf16 v[70:73], v[172:175], v[220:223], v[70:73]
	v_mfma_f32_16x16x32_bf16 v[66:69], v[180:183], v[220:223], v[66:69]
	s_barrier
	s_add_i32 s45, s61, s3
	s_mov_b32 m0, s45
	ds_read_b128 v[184:187], v193 offset:16384
	ds_read_b128 v[196:199], v193 offset:17408
	ds_read_b128 v[200:203], v193 offset:18432
	ds_read_b128 v[204:207], v193 offset:19456
	ds_read_b128 v[208:211], v193 offset:20480
	ds_read_b128 v[212:215], v193 offset:21504
	ds_read_b128 v[216:219], v193 offset:22528
	ds_read_b128 v[220:223], v193 offset:23552
	global_load_lds_dwordx4 v156, s[40:41]
	s_add_i32 m0, s45, 0x2000
	s_add_u32 s46, s40, 0x80000
	s_addc_u32 s47, s41, 0
	s_add_i32 s45, s62, s3
	global_load_lds_dwordx4 v160, s[40:41]
	s_mov_b32 m0, s45
	s_nop 0
	global_load_lds_dwordx4 v156, s[46:47]
	s_add_i32 m0, s45, 0x2000
	s_nop 0
	global_load_lds_dwordx4 v160, s[46:47]
	s_mov_b32 m0, s33
	s_nop 0
	global_load_lds_dwordx4 v162, s[42:43]
	s_mov_b32 m0, s35
	s_nop 0
	global_load_lds_dwordx4 v164, s[42:43]
	s_waitcnt vmcnt(8)
	s_waitcnt lgkmcnt(0)
	s_barrier
	s_waitcnt lgkmcnt(0)
	v_mfma_f32_16x16x32_bf16 v[62:65], v[134:137], v[184:187], 0
	v_mfma_f32_16x16x32_bf16 v[58:61], v[142:145], v[184:187], 0
	v_mfma_f32_16x16x32_bf16 v[46:49], v[134:137], v[200:203], 0
	v_mfma_f32_16x16x32_bf16 v[42:45], v[142:145], v[200:203], 0
	v_mfma_f32_16x16x32_bf16 v[30:33], v[134:137], v[208:211], 0
	v_mfma_f32_16x16x32_bf16 v[26:29], v[142:145], v[208:211], 0
	v_mfma_f32_16x16x32_bf16 v[14:17], v[134:137], v[216:219], 0
	v_mfma_f32_16x16x32_bf16 v[10:13], v[142:145], v[216:219], 0
	v_mfma_f32_16x16x32_bf16 v[62:65], v[138:141], v[196:199], v[62:65]
	v_mfma_f32_16x16x32_bf16 v[58:61], v[146:149], v[196:199], v[58:61]
	v_mfma_f32_16x16x32_bf16 v[46:49], v[138:141], v[204:207], v[46:49]
	v_mfma_f32_16x16x32_bf16 v[42:45], v[146:149], v[204:207], v[42:45]
	v_mfma_f32_16x16x32_bf16 v[30:33], v[138:141], v[212:215], v[30:33]
	v_mfma_f32_16x16x32_bf16 v[26:29], v[146:149], v[212:215], v[26:29]
	v_mfma_f32_16x16x32_bf16 v[14:17], v[138:141], v[220:223], v[14:17]
	v_mfma_f32_16x16x32_bf16 v[10:13], v[146:149], v[220:223], v[10:13]
	v_mfma_f32_16x16x32_bf16 v[54:57], v[150:153], v[184:187], 0
	v_mfma_f32_16x16x32_bf16 v[50:53], v[176:179], v[184:187], 0
	v_mfma_f32_16x16x32_bf16 v[38:41], v[150:153], v[200:203], 0
	v_mfma_f32_16x16x32_bf16 v[34:37], v[176:179], v[200:203], 0
	v_mfma_f32_16x16x32_bf16 v[22:25], v[150:153], v[208:211], 0
	v_mfma_f32_16x16x32_bf16 v[18:21], v[176:179], v[208:211], 0
	v_mfma_f32_16x16x32_bf16 v[6:9], v[150:153], v[216:219], 0
	v_mfma_f32_16x16x32_bf16 v[2:5], v[176:179], v[216:219], 0
	v_mfma_f32_16x16x32_bf16 v[54:57], v[172:175], v[196:199], v[54:57]
	v_mfma_f32_16x16x32_bf16 v[50:53], v[180:183], v[196:199], v[50:53]
	v_mfma_f32_16x16x32_bf16 v[38:41], v[172:175], v[204:207], v[38:41]
	v_mfma_f32_16x16x32_bf16 v[34:37], v[180:183], v[204:207], v[34:37]
	v_mfma_f32_16x16x32_bf16 v[22:25], v[172:175], v[212:215], v[22:25]
	v_mfma_f32_16x16x32_bf16 v[18:21], v[180:183], v[212:215], v[18:21]
	v_mfma_f32_16x16x32_bf16 v[6:9], v[172:175], v[220:223], v[6:9]
	v_mfma_f32_16x16x32_bf16 v[2:5], v[180:183], v[220:223], v[2:5]
	s_barrier
; #define PG8_STAGE(bufoff, gbase, RR, ld) do { _Pragma("unroll") for (int _i = 0; _i < 2; ++_i) \
;         __builtin_amdgcn_global_load_lds((const unsigned*)((const char*)(gbase) + (RR)[_i] * (ld) + C2[_i]), (LAS unsigned*)(lds + (bufoff) + ldsw + _i * 8192), 16, 0, 0); } while (0)
; #define PG8_LDA(dst, b, h) do { _Pragma("unroll") for (int m = 0; m < 4; ++m) _Pragma("unroll") for (int k = 0; k < 2; ++k) dst[m][k] = *(const LAS bf16x8*)(lds + PG8_SA(b, h) + aoff + m * 2048 + k * 1024); } while (0)
; #define PG8_LDB(dst, b, h) do { _Pragma("unroll") for (int n = 0; n < 2; ++n) _Pragma("unroll") for (int k = 0; k < 2; ++k) dst[n][k] = *(const LAS bf16x8*)(lds + PG8_SB(b, h) + boff + n * 2048 + k * 1024); } while (0)
; #define PG8_MMA(ai, bj, At, Bt) do { __builtin_amdgcn_s_setprio(1); _Pragma("unroll") for (int m = 0; m < 4; ++m) _Pragma("unroll") for (int n = 0; n < 2; ++n) _Pragma("unroll") for (int k = 0; k < 2; ++k) \
;         acc[ai][bj][m][n] = __builtin_amdgcn_mfma_f32_16x16x32_bf16(Bt[n][k], At[m][k], acc[ai][bj][m][n], 0, 0, 0); __builtin_amdgcn_s_setprio(0); } while (0)
; #define PG8_WAIT_V(n) asm volatile("s_waitcnt vmcnt(" #n ")" ::: "memory")
; #define PG8_WAIT_L(n) asm volatile("s_waitcnt lgkmcnt(" #n ")" ::: "memory")
; #define PG8_BAR __builtin_amdgcn_s_barrier()
; #define PG8_SCHED __builtin_amdgcn_sched_barrier(0)
; template <class Sched, class Epi>
; __device__ __forceinline__ void gemm_run(LAS unsigned char* lds, const Sched& S, const Epi& E) {
;     ...
;             PG8_LDB(B0, 1, 0); PG8_LDB(B1, 1, 1); PG8_SCHED; PG8_LDA(At, 1, 0); PG8_STAGE(PG8_SA(0, 1), a2 + (size_t)HALF * la2, RA, la2);
;             PG8_WAIT_V(8); PG8_WAIT_L(0); PG8_BAR; PG8_MMA(0, 0, At, B0); PG8_MMA(0, 1, At, B1); PG8_BAR; PG8_SCHED;
;             PG8_LDA(At, 1, 1); PG8_STAGE(PG8_SB(1, 0), b3, RB, lb2); PG8_STAGE(PG8_SB(1, 1), b3 + (size_t)HALF * lb2, RB, lb2); PG8_STAGE(PG8_SA(1, 0), a3, RA, la2);
;             PG8_WAIT_V(8); PG8_WAIT_L(0); PG8_BAR; PG8_MMA(1, 0, At, B0); PG8_MMA(1, 1, At, B1); PG8_BAR; PG8_SCHED;
	s_add_i32 s45, 0, 0x18000
	s_add_i32 s46, 0, 0x1c000
	v_add_u32_e32 v146, s45, v190
	v_add_u32_e32 v180, s46, v190
	ds_read_b128 v[134:137], v146
	ds_read_b128 v[138:141], v146 offset:1024
	ds_read_b128 v[142:145], v146 offset:2048
	ds_read_b128 v[146:149], v146 offset:3072
	ds_read_b128 v[150:153], v180
	ds_read_b128 v[172:175], v180 offset:1024
	ds_read_b128 v[176:179], v180 offset:2048
	ds_read_b128 v[180:183], v180 offset:3072
	s_add_u32 s42, s42, 0x80000
	s_addc_u32 s43, s43, 0
	s_mov_b32 m0, s52
	ds_read_b128 v[184:187], v193 offset:32768
	ds_read_b128 v[196:199], v193 offset:33792
	ds_read_b128 v[200:203], v193 offset:34816
	ds_read_b128 v[204:207], v193 offset:35840
	ds_read_b128 v[208:211], v193 offset:36864
	ds_read_b128 v[212:215], v193 offset:37888
	ds_read_b128 v[216:219], v193 offset:38912
	ds_read_b128 v[220:223], v193 offset:39936
	global_load_lds_dwordx4 v162, s[42:43]
	s_mov_b32 m0, s53
	s_nop 0
	global_load_lds_dwordx4 v164, s[42:43]
	s_waitcnt vmcnt(8)
	s_waitcnt lgkmcnt(0)
	s_barrier
	s_waitcnt lgkmcnt(0)
	v_mfma_f32_16x16x32_bf16 v[126:129], v[134:137], v[184:187], v[126:129]
	v_mfma_f32_16x16x32_bf16 v[122:125], v[142:145], v[184:187], v[122:125]
	v_mfma_f32_16x16x32_bf16 v[110:113], v[134:137], v[200:203], v[110:113]
	v_mfma_f32_16x16x32_bf16 v[106:109], v[142:145], v[200:203], v[106:109]
	v_mfma_f32_16x16x32_bf16 v[94:97], v[134:137], v[208:211], v[94:97]
	v_mfma_f32_16x16x32_bf16 v[90:93], v[142:145], v[208:211], v[90:93]
	v_mfma_f32_16x16x32_bf16 v[78:81], v[134:137], v[216:219], v[78:81]
	v_mfma_f32_16x16x32_bf16 v[74:77], v[142:145], v[216:219], v[74:77]
	v_mfma_f32_16x16x32_bf16 v[126:129], v[138:141], v[196:199], v[126:129]
	v_mfma_f32_16x16x32_bf16 v[122:125], v[146:149], v[196:199], v[122:125]
	v_mfma_f32_16x16x32_bf16 v[110:113], v[138:141], v[204:207], v[110:113]
	v_mfma_f32_16x16x32_bf16 v[106:109], v[146:149], v[204:207], v[106:109]
	v_mfma_f32_16x16x32_bf16 v[94:97], v[138:141], v[212:215], v[94:97]
	v_mfma_f32_16x16x32_bf16 v[90:93], v[146:149], v[212:215], v[90:93]
	v_mfma_f32_16x16x32_bf16 v[78:81], v[138:141], v[220:223], v[78:81]
	v_mfma_f32_16x16x32_bf16 v[74:77], v[146:149], v[220:223], v[74:77]
	v_mfma_f32_16x16x32_bf16 v[118:121], v[150:153], v[184:187], v[118:121]
	v_mfma_f32_16x16x32_bf16 v[114:117], v[176:179], v[184:187], v[114:117]
	v_mfma_f32_16x16x32_bf16 v[102:105], v[150:153], v[200:203], v[102:105]
	v_mfma_f32_16x16x32_bf16 v[98:101], v[176:179], v[200:203], v[98:101]
	v_mfma_f32_16x16x32_bf16 v[86:89], v[150:153], v[208:211], v[86:89]
	v_mfma_f32_16x16x32_bf16 v[82:85], v[176:179], v[208:211], v[82:85]
	v_mfma_f32_16x16x32_bf16 v[70:73], v[150:153], v[216:219], v[70:73]
	v_mfma_f32_16x16x32_bf16 v[66:69], v[176:179], v[216:219], v[66:69]
	v_mfma_f32_16x16x32_bf16 v[118:121], v[172:175], v[196:199], v[118:121]
	v_mfma_f32_16x16x32_bf16 v[114:117], v[180:183], v[196:199], v[114:117]
	v_mfma_f32_16x16x32_bf16 v[102:105], v[172:175], v[204:207], v[102:105]
	v_mfma_f32_16x16x32_bf16 v[98:101], v[180:183], v[204:207], v[98:101]
	v_mfma_f32_16x16x32_bf16 v[86:89], v[172:175], v[212:215], v[86:89]
	v_mfma_f32_16x16x32_bf16 v[82:85], v[180:183], v[212:215], v[82:85]
	v_mfma_f32_16x16x32_bf16 v[70:73], v[172:175], v[220:223], v[70:73]
	v_mfma_f32_16x16x32_bf16 v[66:69], v[180:183], v[220:223], v[66:69]
	s_barrier
	s_add_i32 s42, s45, s3
	s_mov_b32 m0, s42
	ds_read_b128 v[184:187], v193 offset:49152
	ds_read_b128 v[196:199], v193 offset:50176
	ds_read_b128 v[200:203], v193 offset:51200
	ds_read_b128 v[204:207], v193 offset:52224
	ds_read_b128 v[208:211], v193 offset:53248
	ds_read_b128 v[212:215], v193 offset:54272
	ds_read_b128 v[216:219], v193 offset:55296
	ds_read_b128 v[220:223], v193 offset:56320
	s_add_u32 s98, s40, 0x80
	s_addc_u32 s99, s41, 0
	global_load_lds_dwordx4 v156, s[98:99]
	s_add_i32 m0, s42, 0x2000
	s_nop 0
	global_load_lds_dwordx4 v160, s[98:99]
	s_add_u32 s40, s40, 0x80080
	s_addc_u32 s41, s41, 0
	s_add_i32 s42, s46, s3
	s_mov_b32 m0, s42
	s_nop 0
	global_load_lds_dwordx4 v156, s[40:41]
	s_add_i32 m0, s42, 0x2000
	s_nop 0
	global_load_lds_dwordx4 v160, s[40:41]
	s_mov_b32 m0, s55
	s_nop 0
	s_add_u32 s100, s100, 0x80
	s_addc_u32 s101, s101, 0
	global_load_lds_dwordx4 v162, s[100:101]
	s_mov_b32 m0, s56
	s_nop 0
	global_load_lds_dwordx4 v164, s[100:101]
	s_waitcnt vmcnt(8)
	s_waitcnt lgkmcnt(0)
	s_barrier
	s_waitcnt lgkmcnt(0)
	v_mfma_f32_16x16x32_bf16 v[62:65], v[134:137], v[184:187], v[62:65]
	v_mfma_f32_16x16x32_bf16 v[58:61], v[142:145], v[184:187], v[58:61]
	v_mfma_f32_16x16x32_bf16 v[46:49], v[134:137], v[200:203], v[46:49]
	v_mfma_f32_16x16x32_bf16 v[42:45], v[142:145], v[200:203], v[42:45]
	v_mfma_f32_16x16x32_bf16 v[30:33], v[134:137], v[208:211], v[30:33]
	v_mfma_f32_16x16x32_bf16 v[26:29], v[142:145], v[208:211], v[26:29]
	v_mfma_f32_16x16x32_bf16 v[14:17], v[134:137], v[216:219], v[14:17]
	v_mfma_f32_16x16x32_bf16 v[10:13], v[142:145], v[216:219], v[10:13]
	v_mfma_f32_16x16x32_bf16 v[62:65], v[138:141], v[196:199], v[62:65]
	v_mfma_f32_16x16x32_bf16 v[58:61], v[146:149], v[196:199], v[58:61]
	v_mfma_f32_16x16x32_bf16 v[46:49], v[138:141], v[204:207], v[46:49]
	v_mfma_f32_16x16x32_bf16 v[42:45], v[146:149], v[204:207], v[42:45]
	v_mfma_f32_16x16x32_bf16 v[30:33], v[138:141], v[212:215], v[30:33]
	v_mfma_f32_16x16x32_bf16 v[26:29], v[146:149], v[212:215], v[26:29]
	v_mfma_f32_16x16x32_bf16 v[14:17], v[138:141], v[220:223], v[14:17]
	v_mfma_f32_16x16x32_bf16 v[10:13], v[146:149], v[220:223], v[10:13]
	v_mfma_f32_16x16x32_bf16 v[54:57], v[150:153], v[184:187], v[54:57]
	v_mfma_f32_16x16x32_bf16 v[50:53], v[176:179], v[184:187], v[50:53]
	v_mfma_f32_16x16x32_bf16 v[38:41], v[150:153], v[200:203], v[38:41]
	v_mfma_f32_16x16x32_bf16 v[34:37], v[176:179], v[200:203], v[34:37]
	v_mfma_f32_16x16x32_bf16 v[22:25], v[150:153], v[208:211], v[22:25]
	v_mfma_f32_16x16x32_bf16 v[18:21], v[176:179], v[208:211], v[18:21]
	v_mfma_f32_16x16x32_bf16 v[6:9], v[150:153], v[216:219], v[6:9]
	v_mfma_f32_16x16x32_bf16 v[2:5], v[176:179], v[216:219], v[2:5]
	v_mfma_f32_16x16x32_bf16 v[54:57], v[172:175], v[196:199], v[54:57]
	v_mfma_f32_16x16x32_bf16 v[50:53], v[180:183], v[196:199], v[50:53]
	v_mfma_f32_16x16x32_bf16 v[38:41], v[172:175], v[204:207], v[38:41]
	v_mfma_f32_16x16x32_bf16 v[34:37], v[180:183], v[204:207], v[34:37]
	v_mfma_f32_16x16x32_bf16 v[22:25], v[172:175], v[212:215], v[22:25]
	v_mfma_f32_16x16x32_bf16 v[18:21], v[180:183], v[212:215], v[18:21]
	v_mfma_f32_16x16x32_bf16 v[6:9], v[172:175], v[220:223], v[6:9]
	v_mfma_f32_16x16x32_bf16 v[2:5], v[180:183], v[220:223], v[2:5]
	s_barrier
	s_add_i32 s44, s44, 2
	s_add_u32 s38, s38, 0x100
	s_addc_u32 s39, s39, 0
	s_cmp_gt_u32 s44, 29
	s_cbranch_scc0 .LBB0_894
	.p2align 6
; #define PG8_STAGE(bufoff, gbase, RR, ld) do { _Pragma("unroll") for (int _i = 0; _i < 2; ++_i) \
;         __builtin_amdgcn_global_load_lds((const unsigned*)((const char*)(gbase) + (RR)[_i] * (ld) + C2[_i]), (LAS unsigned*)(lds + (bufoff) + ldsw + _i * 8192), 16, 0, 0); } while (0)
; #define PG8_LDA(dst, b, h) do { _Pragma("unroll") for (int m = 0; m < 4; ++m) _Pragma("unroll") for (int k = 0; k < 2; ++k) dst[m][k] = *(const LAS bf16x8*)(lds + PG8_SA(b, h) + aoff + m * 2048 + k * 1024); } while (0)
; #define PG8_LDB(dst, b, h) do { _Pragma("unroll") for (int n = 0; n < 2; ++n) _Pragma("unroll") for (int k = 0; k < 2; ++k) dst[n][k] = *(const LAS bf16x8*)(lds + PG8_SB(b, h) + boff + n * 2048 + k * 1024); } while (0)
; #define PG8_MMA(ai, bj, At, Bt) do { __builtin_amdgcn_s_setprio(1); _Pragma("unroll") for (int m = 0; m < 4; ++m) _Pragma("unroll") for (int n = 0; n < 2; ++n) _Pragma("unroll") for (int k = 0; k < 2; ++k) \
;         acc[ai][bj][m][n] = __builtin_amdgcn_mfma_f32_16x16x32_bf16(Bt[n][k], At[m][k], acc[ai][bj][m][n], 0, 0, 0); __builtin_amdgcn_s_setprio(0); } while (0)
; #define PG8_WAIT_V(n) asm volatile("s_waitcnt vmcnt(" #n ")" ::: "memory")
; #define PG8_WAIT_L(n) asm volatile("s_waitcnt lgkmcnt(" #n ")" ::: "memory")
; template <class Sched, class Epi>
; __device__ __forceinline__ void gemm_run(LAS unsigned char* lds, const Sched& S, const Epi& E) {
;     ...
;         for (int t = 0; t < nt; t += 2) {
;             const bool last = (t == nt - 2);
;             const char* a1 = cA + (size_t)(t + 1) * kstep;
;             const char* a2 = last ? nA : cA + (size_t)(t + 2) * kstep; const char* b2 = last ? nB : cB + (size_t)(t + 2) * kstep;
;             const unsigned la2 = last ? nlda : lda, lb2 = last ? nldb : ldb;
;             const char* a3 = a2 + kstep; const char* b3 = b2 + kstep;
;             PG8_LDB(B0, 0, 0); PG8_LDB(B1, 0, 1); PG8_SCHED; PG8_LDA(At, 0, 0); PG8_STAGE(PG8_SA(1, 1), a1 + (size_t)HALF * lda, RA, lda);
;             PG8_WAIT_V(8); PG8_WAIT_L(0); PG8_BAR; PG8_MMA(0, 0, At, B0); PG8_MMA(0, 1, At, B1); PG8_BAR; PG8_SCHED;
;             PG8_LDA(At, 0, 1); PG8_STAGE(PG8_SB(0, 0), b2, RB, lb2); PG8_STAGE(PG8_SB(0, 1), b2 + (size_t)HALF * lb2, RB, lb2); PG8_STAGE(PG8_SA(0, 0), a2, RA, la2);
;             PG8_WAIT_V(8); PG8_WAIT_L(0); PG8_BAR; PG8_MMA(1, 0, At, B0); PG8_MMA(1, 1, At, B1); PG8_BAR; PG8_SCHED;
.LBB0_894:
	ds_read_b128 v[134:137], v191
	ds_read_b128 v[138:141], v191 offset:1024
	ds_read_b128 v[142:145], v191 offset:2048
	ds_read_b128 v[146:149], v191 offset:3072
	ds_read_b128 v[150:153], v192
	ds_read_b128 v[172:175], v192 offset:1024
	ds_read_b128 v[176:179], v192 offset:2048
	ds_read_b128 v[180:183], v192 offset:3072
	s_add_u32 s40, s36, s38
	s_addc_u32 s41, s37, s39
	s_mov_b32 s98, s40
	s_mov_b32 s99, s41
	s_add_u32 s40, s40, 0x100
	s_addc_u32 s41, s41, 0
	s_add_u32 s45, s19, s38
	s_addc_u32 s46, s31, s39
	s_cmpk_eq_i32 s38, 0xf00
	s_cselect_b32 s43, s21, s41
	s_cselect_b32 s42, s20, s40
	s_cselect_b32 s41, s29, s46
	s_cselect_b32 s40, s28, s45
	s_mov_b64 s[100:101], s[42:43]
	s_add_i32 m0, s33, 0xc000
	ds_read_b128 v[184:187], v193
	ds_read_b128 v[196:199], v193 offset:1024
	ds_read_b128 v[200:203], v193 offset:2048
	ds_read_b128 v[204:207], v193 offset:3072
	ds_read_b128 v[208:211], v193 offset:4096
	ds_read_b128 v[212:215], v193 offset:5120
	ds_read_b128 v[216:219], v193 offset:6144
	ds_read_b128 v[220:223], v193 offset:7168
	global_load_lds_dwordx4 v168, s[98:99]
	s_add_i32 m0, s33, 0xe000
	s_nop 0
	global_load_lds_dwordx4 v170, s[98:99]
	s_waitcnt vmcnt(8)
	s_waitcnt lgkmcnt(0)
	s_barrier
	s_waitcnt lgkmcnt(0)
	v_mfma_f32_16x16x32_bf16 v[126:129], v[134:137], v[184:187], v[126:129]
	v_mfma_f32_16x16x32_bf16 v[122:125], v[142:145], v[184:187], v[122:125]
	v_mfma_f32_16x16x32_bf16 v[110:113], v[134:137], v[200:203], v[110:113]
	v_mfma_f32_16x16x32_bf16 v[106:109], v[142:145], v[200:203], v[106:109]
	v_mfma_f32_16x16x32_bf16 v[94:97], v[134:137], v[208:211], v[94:97]
	v_mfma_f32_16x16x32_bf16 v[90:93], v[142:145], v[208:211], v[90:93]
	v_mfma_f32_16x16x32_bf16 v[78:81], v[134:137], v[216:219], v[78:81]
	v_mfma_f32_16x16x32_bf16 v[74:77], v[142:145], v[216:219], v[74:77]
	v_mfma_f32_16x16x32_bf16 v[126:129], v[138:141], v[196:199], v[126:129]
	v_mfma_f32_16x16x32_bf16 v[122:125], v[146:149], v[196:199], v[122:125]
	v_mfma_f32_16x16x32_bf16 v[110:113], v[138:141], v[204:207], v[110:113]
	v_mfma_f32_16x16x32_bf16 v[106:109], v[146:149], v[204:207], v[106:109]
	v_mfma_f32_16x16x32_bf16 v[94:97], v[138:141], v[212:215], v[94:97]
	v_mfma_f32_16x16x32_bf16 v[90:93], v[146:149], v[212:215], v[90:93]
	v_mfma_f32_16x16x32_bf16 v[78:81], v[138:141], v[220:223], v[78:81]
	v_mfma_f32_16x16x32_bf16 v[74:77], v[146:149], v[220:223], v[74:77]
	v_mfma_f32_16x16x32_bf16 v[118:121], v[150:153], v[184:187], v[118:121]
	v_mfma_f32_16x16x32_bf16 v[114:117], v[176:179], v[184:187], v[114:117]
	v_mfma_f32_16x16x32_bf16 v[102:105], v[150:153], v[200:203], v[102:105]
	v_mfma_f32_16x16x32_bf16 v[98:101], v[176:179], v[200:203], v[98:101]
	v_mfma_f32_16x16x32_bf16 v[86:89], v[150:153], v[208:211], v[86:89]
	v_mfma_f32_16x16x32_bf16 v[82:85], v[176:179], v[208:211], v[82:85]
	v_mfma_f32_16x16x32_bf16 v[70:73], v[150:153], v[216:219], v[70:73]
	v_mfma_f32_16x16x32_bf16 v[66:69], v[176:179], v[216:219], v[66:69]
	v_mfma_f32_16x16x32_bf16 v[118:121], v[172:175], v[196:199], v[118:121]
	v_mfma_f32_16x16x32_bf16 v[114:117], v[180:183], v[196:199], v[114:117]
	v_mfma_f32_16x16x32_bf16 v[102:105], v[172:175], v[204:207], v[102:105]
	v_mfma_f32_16x16x32_bf16 v[98:101], v[180:183], v[204:207], v[98:101]
	v_mfma_f32_16x16x32_bf16 v[86:89], v[172:175], v[212:215], v[86:89]
	v_mfma_f32_16x16x32_bf16 v[82:85], v[180:183], v[212:215], v[82:85]
	v_mfma_f32_16x16x32_bf16 v[70:73], v[172:175], v[220:223], v[70:73]
	v_mfma_f32_16x16x32_bf16 v[66:69], v[180:183], v[220:223], v[66:69]
	s_barrier
	s_add_i32 s45, s61, s3
	s_mov_b32 m0, s45
	ds_read_b128 v[184:187], v193 offset:16384
	ds_read_b128 v[196:199], v193 offset:17408
	ds_read_b128 v[200:203], v193 offset:18432
	ds_read_b128 v[204:207], v193 offset:19456
	ds_read_b128 v[208:211], v193 offset:20480
	ds_read_b128 v[212:215], v193 offset:21504
	ds_read_b128 v[216:219], v193 offset:22528
	ds_read_b128 v[220:223], v193 offset:23552
	global_load_lds_dwordx4 v156, s[40:41]
	s_add_i32 m0, s45, 0x2000
	s_add_u32 s46, s40, 0x80000
	s_addc_u32 s47, s41, 0
	s_add_i32 s45, s62, s3
	global_load_lds_dwordx4 v160, s[40:41]
	s_mov_b32 m0, s45
	s_nop 0
	global_load_lds_dwordx4 v156, s[46:47]
	s_add_i32 m0, s45, 0x2000
	s_nop 0
	global_load_lds_dwordx4 v160, s[46:47]
	s_mov_b32 m0, s33
	s_nop 0
	global_load_lds_dwordx4 v162, s[42:43]
	s_mov_b32 m0, s35
	s_nop 0
	global_load_lds_dwordx4 v164, s[42:43]
	s_waitcnt vmcnt(8)
	s_waitcnt lgkmcnt(0)
	s_barrier
	s_waitcnt lgkmcnt(0)
	v_mfma_f32_16x16x32_bf16 v[62:65], v[134:137], v[184:187], v[62:65]
	v_mfma_f32_16x16x32_bf16 v[58:61], v[142:145], v[184:187], v[58:61]
	v_mfma_f32_16x16x32_bf16 v[46:49], v[134:137], v[200:203], v[46:49]
	v_mfma_f32_16x16x32_bf16 v[42:45], v[142:145], v[200:203], v[42:45]
	v_mfma_f32_16x16x32_bf16 v[30:33], v[134:137], v[208:211], v[30:33]
	v_mfma_f32_16x16x32_bf16 v[26:29], v[142:145], v[208:211], v[26:29]
	v_mfma_f32_16x16x32_bf16 v[14:17], v[134:137], v[216:219], v[14:17]
	v_mfma_f32_16x16x32_bf16 v[10:13], v[142:145], v[216:219], v[10:13]
	v_mfma_f32_16x16x32_bf16 v[62:65], v[138:141], v[196:199], v[62:65]
	v_mfma_f32_16x16x32_bf16 v[58:61], v[146:149], v[196:199], v[58:61]
	v_mfma_f32_16x16x32_bf16 v[46:49], v[138:141], v[204:207], v[46:49]
	v_mfma_f32_16x16x32_bf16 v[42:45], v[146:149], v[204:207], v[42:45]
	v_mfma_f32_16x16x32_bf16 v[30:33], v[138:141], v[212:215], v[30:33]
	v_mfma_f32_16x16x32_bf16 v[26:29], v[146:149], v[212:215], v[26:29]
	v_mfma_f32_16x16x32_bf16 v[14:17], v[138:141], v[220:223], v[14:17]
	v_mfma_f32_16x16x32_bf16 v[10:13], v[146:149], v[220:223], v[10:13]
	v_mfma_f32_16x16x32_bf16 v[54:57], v[150:153], v[184:187], v[54:57]
	v_mfma_f32_16x16x32_bf16 v[50:53], v[176:179], v[184:187], v[50:53]
	v_mfma_f32_16x16x32_bf16 v[38:41], v[150:153], v[200:203], v[38:41]
	v_mfma_f32_16x16x32_bf16 v[34:37], v[176:179], v[200:203], v[34:37]
	v_mfma_f32_16x16x32_bf16 v[22:25], v[150:153], v[208:211], v[22:25]
	v_mfma_f32_16x16x32_bf16 v[18:21], v[176:179], v[208:211], v[18:21]
	v_mfma_f32_16x16x32_bf16 v[6:9], v[150:153], v[216:219], v[6:9]
	v_mfma_f32_16x16x32_bf16 v[2:5], v[176:179], v[216:219], v[2:5]
	v_mfma_f32_16x16x32_bf16 v[54:57], v[172:175], v[196:199], v[54:57]
	v_mfma_f32_16x16x32_bf16 v[50:53], v[180:183], v[196:199], v[50:53]
	v_mfma_f32_16x16x32_bf16 v[38:41], v[172:175], v[204:207], v[38:41]
	v_mfma_f32_16x16x32_bf16 v[34:37], v[180:183], v[204:207], v[34:37]
	v_mfma_f32_16x16x32_bf16 v[22:25], v[172:175], v[212:215], v[22:25]
	v_mfma_f32_16x16x32_bf16 v[18:21], v[180:183], v[212:215], v[18:21]
	v_mfma_f32_16x16x32_bf16 v[6:9], v[172:175], v[220:223], v[6:9]
	v_mfma_f32_16x16x32_bf16 v[2:5], v[180:183], v[220:223], v[2:5]
	s_barrier
; #define PG8_STAGE(bufoff, gbase, RR, ld) do { _Pragma("unroll") for (int _i = 0; _i < 2; ++_i) \
;         __builtin_amdgcn_global_load_lds((const unsigned*)((const char*)(gbase) + (RR)[_i] * (ld) + C2[_i]), (LAS unsigned*)(lds + (bufoff) + ldsw + _i * 8192), 16, 0, 0); } while (0)
; #define PG8_LDA(dst, b, h) do { _Pragma("unroll") for (int m = 0; m < 4; ++m) _Pragma("unroll") for (int k = 0; k < 2; ++k) dst[m][k] = *(const LAS bf16x8*)(lds + PG8_SA(b, h) + aoff + m * 2048 + k * 1024); } while (0)
; #define PG8_LDB(dst, b, h) do { _Pragma("unroll") for (int n = 0; n < 2; ++n) _Pragma("unroll") for (int k = 0; k < 2; ++k) dst[n][k] = *(const LAS bf16x8*)(lds + PG8_SB(b, h) + boff + n * 2048 + k * 1024); } while (0)
; #define PG8_MMA(ai, bj, At, Bt) do { __builtin_amdgcn_s_setprio(1); _Pragma("unroll") for (int m = 0; m < 4; ++m) _Pragma("unroll") for (int n = 0; n < 2; ++n) _Pragma("unroll") for (int k = 0; k < 2; ++k) \
;         acc[ai][bj][m][n] = __builtin_amdgcn_mfma_f32_16x16x32_bf16(Bt[n][k], At[m][k], acc[ai][bj][m][n], 0, 0, 0); __builtin_amdgcn_s_setprio(0); } while (0)
; #define PG8_WAIT_V(n) asm volatile("s_waitcnt vmcnt(" #n ")" ::: "memory")
; #define PG8_WAIT_L(n) asm volatile("s_waitcnt lgkmcnt(" #n ")" ::: "memory")
; #define PG8_BAR __builtin_amdgcn_s_barrier()
; #define PG8_SCHED __builtin_amdgcn_sched_barrier(0)
; template <class Sched, class Epi>
; __device__ __forceinline__ void gemm_run(LAS unsigned char* lds, const Sched& S, const Epi& E) {
;     ...
;             PG8_LDB(B0, 1, 0); PG8_LDB(B1, 1, 1); PG8_SCHED; PG8_LDA(At, 1, 0); PG8_STAGE(PG8_SA(0, 1), a2 + (size_t)HALF * la2, RA, la2);
;             PG8_WAIT_V(8); PG8_WAIT_L(0); PG8_BAR; PG8_MMA(0, 0, At, B0); PG8_MMA(0, 1, At, B1); PG8_BAR; PG8_SCHED;
;             PG8_LDA(At, 1, 1); PG8_STAGE(PG8_SB(1, 0), b3, RB, lb2); PG8_STAGE(PG8_SB(1, 1), b3 + (size_t)HALF * lb2, RB, lb2); PG8_STAGE(PG8_SA(1, 0), a3, RA, la2);
;             PG8_WAIT_V(8); PG8_WAIT_L(0); PG8_BAR; PG8_MMA(1, 0, At, B0); PG8_MMA(1, 1, At, B1); PG8_BAR; PG8_SCHED;
;         }
;         if (wr == 0) PG8_BAR;
	s_add_i32 s45, 0, 0x18000
	s_add_i32 s46, 0, 0x1c000
	v_add_u32_e32 v146, s45, v190
	v_add_u32_e32 v180, s46, v190
	ds_read_b128 v[134:137], v146
	ds_read_b128 v[138:141], v146 offset:1024
	ds_read_b128 v[142:145], v146 offset:2048
	ds_read_b128 v[146:149], v146 offset:3072
	ds_read_b128 v[150:153], v180
	ds_read_b128 v[172:175], v180 offset:1024
	ds_read_b128 v[176:179], v180 offset:2048
	ds_read_b128 v[180:183], v180 offset:3072
	s_add_u32 s42, s42, 0x80000
	s_addc_u32 s43, s43, 0
	s_mov_b32 m0, s52
	ds_read_b128 v[184:187], v193 offset:32768
	ds_read_b128 v[196:199], v193 offset:33792
	ds_read_b128 v[200:203], v193 offset:34816
	ds_read_b128 v[204:207], v193 offset:35840
	ds_read_b128 v[208:211], v193 offset:36864
	ds_read_b128 v[212:215], v193 offset:37888
	ds_read_b128 v[216:219], v193 offset:38912
	ds_read_b128 v[220:223], v193 offset:39936
	global_load_lds_dwordx4 v162, s[42:43]
	s_mov_b32 m0, s53
	s_nop 0
	global_load_lds_dwordx4 v164, s[42:43]
	s_waitcnt vmcnt(8)
	s_waitcnt lgkmcnt(0)
	s_barrier
	s_waitcnt lgkmcnt(0)
	v_mfma_f32_16x16x32_bf16 v[126:129], v[134:137], v[184:187], v[126:129]
	v_mfma_f32_16x16x32_bf16 v[122:125], v[142:145], v[184:187], v[122:125]
	v_mfma_f32_16x16x32_bf16 v[110:113], v[134:137], v[200:203], v[110:113]
	v_mfma_f32_16x16x32_bf16 v[106:109], v[142:145], v[200:203], v[106:109]
	v_mfma_f32_16x16x32_bf16 v[94:97], v[134:137], v[208:211], v[94:97]
	v_mfma_f32_16x16x32_bf16 v[90:93], v[142:145], v[208:211], v[90:93]
	v_mfma_f32_16x16x32_bf16 v[78:81], v[134:137], v[216:219], v[78:81]
	v_mfma_f32_16x16x32_bf16 v[74:77], v[142:145], v[216:219], v[74:77]
	v_mfma_f32_16x16x32_bf16 v[126:129], v[138:141], v[196:199], v[126:129]
	v_mfma_f32_16x16x32_bf16 v[122:125], v[146:149], v[196:199], v[122:125]
	v_mfma_f32_16x16x32_bf16 v[110:113], v[138:141], v[204:207], v[110:113]
	v_mfma_f32_16x16x32_bf16 v[106:109], v[146:149], v[204:207], v[106:109]
	v_mfma_f32_16x16x32_bf16 v[94:97], v[138:141], v[212:215], v[94:97]
	v_mfma_f32_16x16x32_bf16 v[90:93], v[146:149], v[212:215], v[90:93]
	v_mfma_f32_16x16x32_bf16 v[78:81], v[138:141], v[220:223], v[78:81]
	v_mfma_f32_16x16x32_bf16 v[74:77], v[146:149], v[220:223], v[74:77]
	v_mfma_f32_16x16x32_bf16 v[118:121], v[150:153], v[184:187], v[118:121]
	v_mfma_f32_16x16x32_bf16 v[114:117], v[176:179], v[184:187], v[114:117]
	v_mfma_f32_16x16x32_bf16 v[102:105], v[150:153], v[200:203], v[102:105]
	v_mfma_f32_16x16x32_bf16 v[98:101], v[176:179], v[200:203], v[98:101]
	v_mfma_f32_16x16x32_bf16 v[86:89], v[150:153], v[208:211], v[86:89]
	v_mfma_f32_16x16x32_bf16 v[82:85], v[176:179], v[208:211], v[82:85]
	v_mfma_f32_16x16x32_bf16 v[70:73], v[150:153], v[216:219], v[70:73]
	v_mfma_f32_16x16x32_bf16 v[66:69], v[176:179], v[216:219], v[66:69]
	v_mfma_f32_16x16x32_bf16 v[118:121], v[172:175], v[196:199], v[118:121]
	v_mfma_f32_16x16x32_bf16 v[114:117], v[180:183], v[196:199], v[114:117]
	v_mfma_f32_16x16x32_bf16 v[102:105], v[172:175], v[204:207], v[102:105]
	v_mfma_f32_16x16x32_bf16 v[98:101], v[180:183], v[204:207], v[98:101]
	v_mfma_f32_16x16x32_bf16 v[86:89], v[172:175], v[212:215], v[86:89]
	v_mfma_f32_16x16x32_bf16 v[82:85], v[180:183], v[212:215], v[82:85]
	v_mfma_f32_16x16x32_bf16 v[70:73], v[172:175], v[220:223], v[70:73]
	v_mfma_f32_16x16x32_bf16 v[66:69], v[180:183], v[220:223], v[66:69]
	s_barrier
	s_add_i32 s42, s45, s3
	s_mov_b32 m0, s42
	ds_read_b128 v[184:187], v193 offset:49152
	ds_read_b128 v[196:199], v193 offset:50176
	ds_read_b128 v[200:203], v193 offset:51200
	ds_read_b128 v[204:207], v193 offset:52224
	ds_read_b128 v[208:211], v193 offset:53248
	ds_read_b128 v[212:215], v193 offset:54272
	ds_read_b128 v[216:219], v193 offset:55296
	ds_read_b128 v[220:223], v193 offset:56320
	s_add_u32 s98, s40, 0x80
	s_addc_u32 s99, s41, 0
	global_load_lds_dwordx4 v156, s[98:99]
	s_add_i32 m0, s42, 0x2000
	s_nop 0
	global_load_lds_dwordx4 v160, s[98:99]
	s_add_u32 s40, s40, 0x80080
	s_addc_u32 s41, s41, 0
	s_add_i32 s42, s46, s3
	s_mov_b32 m0, s42
	s_nop 0
	global_load_lds_dwordx4 v156, s[40:41]
	s_add_i32 m0, s42, 0x2000
	s_nop 0
	global_load_lds_dwordx4 v160, s[40:41]
	s_mov_b32 m0, s55
	s_nop 0
	s_add_u32 s100, s100, 0x80
	s_addc_u32 s101, s101, 0
	global_load_lds_dwordx4 v162, s[100:101]
	s_mov_b32 m0, s56
	s_nop 0
	global_load_lds_dwordx4 v164, s[100:101]
	s_waitcnt vmcnt(8)
	s_waitcnt lgkmcnt(0)
	s_barrier
	s_waitcnt lgkmcnt(0)
	v_mfma_f32_16x16x32_bf16 v[62:65], v[134:137], v[184:187], v[62:65]
	v_mfma_f32_16x16x32_bf16 v[58:61], v[142:145], v[184:187], v[58:61]
	v_mfma_f32_16x16x32_bf16 v[46:49], v[134:137], v[200:203], v[46:49]
	v_mfma_f32_16x16x32_bf16 v[42:45], v[142:145], v[200:203], v[42:45]
	v_mfma_f32_16x16x32_bf16 v[30:33], v[134:137], v[208:211], v[30:33]
	v_mfma_f32_16x16x32_bf16 v[26:29], v[142:145], v[208:211], v[26:29]
	v_mfma_f32_16x16x32_bf16 v[14:17], v[134:137], v[216:219], v[14:17]
	v_mfma_f32_16x16x32_bf16 v[10:13], v[142:145], v[216:219], v[10:13]
	v_mfma_f32_16x16x32_bf16 v[62:65], v[138:141], v[196:199], v[62:65]
	v_mfma_f32_16x16x32_bf16 v[58:61], v[146:149], v[196:199], v[58:61]
	v_mfma_f32_16x16x32_bf16 v[46:49], v[138:141], v[204:207], v[46:49]
	v_mfma_f32_16x16x32_bf16 v[42:45], v[146:149], v[204:207], v[42:45]
	v_mfma_f32_16x16x32_bf16 v[30:33], v[138:141], v[212:215], v[30:33]
	v_mfma_f32_16x16x32_bf16 v[26:29], v[146:149], v[212:215], v[26:29]
	v_mfma_f32_16x16x32_bf16 v[14:17], v[138:141], v[220:223], v[14:17]
	v_mfma_f32_16x16x32_bf16 v[10:13], v[146:149], v[220:223], v[10:13]
	v_mfma_f32_16x16x32_bf16 v[54:57], v[150:153], v[184:187], v[54:57]
	v_mfma_f32_16x16x32_bf16 v[50:53], v[176:179], v[184:187], v[50:53]
	v_mfma_f32_16x16x32_bf16 v[38:41], v[150:153], v[200:203], v[38:41]
	v_mfma_f32_16x16x32_bf16 v[34:37], v[176:179], v[200:203], v[34:37]
	v_mfma_f32_16x16x32_bf16 v[22:25], v[150:153], v[208:211], v[22:25]
	v_mfma_f32_16x16x32_bf16 v[18:21], v[176:179], v[208:211], v[18:21]
	v_mfma_f32_16x16x32_bf16 v[6:9], v[150:153], v[216:219], v[6:9]
	v_mfma_f32_16x16x32_bf16 v[2:5], v[176:179], v[216:219], v[2:5]
	v_mfma_f32_16x16x32_bf16 v[54:57], v[172:175], v[196:199], v[54:57]
	v_mfma_f32_16x16x32_bf16 v[50:53], v[180:183], v[196:199], v[50:53]
	v_mfma_f32_16x16x32_bf16 v[38:41], v[172:175], v[204:207], v[38:41]
	v_mfma_f32_16x16x32_bf16 v[34:37], v[180:183], v[204:207], v[34:37]
	v_mfma_f32_16x16x32_bf16 v[22:25], v[172:175], v[212:215], v[22:25]
	v_mfma_f32_16x16x32_bf16 v[18:21], v[180:183], v[212:215], v[18:21]
	v_mfma_f32_16x16x32_bf16 v[6:9], v[172:175], v[220:223], v[6:9]
	v_mfma_f32_16x16x32_bf16 v[2:5], v[180:183], v[220:223], v[2:5]
	s_barrier
	s_add_i32 s44, s44, 2
	s_add_u32 s38, s38, 0x100
	s_addc_u32 s39, s39, 0
	s_cmp_gt_u32 s44, 29
	s_cbranch_scc0 .LBB0_894
	s_and_b64 vcc, exec, s[12:13]
	s_cbranch_vccz .LBB0_897
	s_barrier

; #define PG8_STAGE(bufoff, gbase, RR, ld) do { _Pragma("unroll") for (int _i = 0; _i < 2; ++_i) \
;         __builtin_amdgcn_global_load_lds((const unsigned*)((const char*)(gbase) + (RR)[_i] * (ld) + C2[_i]), (LAS unsigned*)(lds + (bufoff) + ldsw + _i * 8192), 16, 0, 0); } while (0)
; #define PG8_WAIT_V(n) asm volatile("s_waitcnt vmcnt(" #n ")" ::: "memory")
; #define PG8_BAR __builtin_amdgcn_s_barrier()
; template <class Sched, class Epi>
; __device__ __forceinline__ void gemm_run(LAS unsigned char* lds, const Sched& S, const Epi& E) {
;     const int tid = threadIdx.x, wid = __builtin_amdgcn_readfirstlane(tid >> 6), lane = tid & 63, wr = wid >> 2, wc = wid & 3, fr = lane & 15, fq = lane >> 4;
;     unsigned RA[2], RB[2], C2[2];
; #pragma unroll
;     for (int i = 0; i < 2; ++i) { int R, C; stage_rc(tid * 16 + i * 8192, R, C); RA[i] = (unsigned)R; RB[i] = (unsigned)((R & ~31) + perm32(R & 31)); C2[i] = (unsigned)(C * 2); }
;     const unsigned ldsw = (unsigned)wid * 1024u;
;     const int aoff = lds_byte(wr * 64 + fr, fq * 8), boff = lds_byte(wc * 32 + fr, fq * 8);
;     ...
;     Unit cur, nxt; int ui = 0;
;     if (!S.next(0, cur)) return;
;     f32x4 acc[2][2][4][2];
; #pragma unroll
;     for (int a = 0; a < 2; ++a)
; #pragma unroll
;         for (int b = 0; b < 2; ++b)
; #pragma unroll
;             for (int m = 0; m < 4; ++m)
; #pragma unroll
;                 for (int n = 0; n < 2; ++n) acc[a][b][m][n] = (f32x4){0.f, 0.f, 0.f, 0.f};
;     bf16x8 At[4][2], B0[2][2], B1[2][2];
;     const char* cA = cur.A; const char* cB = cur.B; unsigned lda = cur.lda, ldb = cur.ldb;
;     constexpr unsigned kstep = BK * 2;
;     PG8_STAGE(PG8_SB(0, 0), cB, RB, ldb); PG8_STAGE(PG8_SB(0, 1), cB + (size_t)HALF * ldb, RB, ldb); PG8_STAGE(PG8_SA(0, 0), cA, RA, lda); PG8_STAGE(PG8_SA(0, 1), cA + (size_t)HALF * lda, RA, lda);
;     if (wr == 1) PG8_BAR;
;     PG8_WAIT_V(2); PG8_BAR;
;     PG8_STAGE(PG8_SB(1, 0), cB + kstep, RB, ldb); PG8_STAGE(PG8_SA(1, 0), cA + kstep, RA, lda); PG8_STAGE(PG8_SB(1, 1), cB + (size_t)HALF * ldb + kstep, RB, ldb);
;     PG8_WAIT_V(6); PG8_BAR;
.LBB0_1064:
	s_and_b32 s33, s10, 3
	s_mov_b64 s[10:11], 0x80
	s_add_i32 m0, s42, 0x18000
	v_lshl_add_u64 v[2:3], v[2:3], 0, s[10:11]
	s_lshl_b32 s46, s1, 6
	s_lshl_b32 s13, s1, 13
	s_lshl_b32 s16, s33, 12
	s_waitcnt vmcnt(2)
	s_barrier
	global_load_lds_dwordx4 v[2:3], off
	v_lshl_add_u64 v[2:3], v[4:5], 0, s[10:11]
	s_add_i32 m0, s42, 0x1a000
	s_add_i32 s47, s42, 0x8000
	s_add_i32 s48, s42, 0xa000
	global_load_lds_dwordx4 v[2:3], off
	v_lshl_add_u64 v[2:3], v[6:7], 0, s[10:11]
	s_mov_b32 m0, s47
	s_add_u32 s14, s28, 0x160080
	global_load_lds_dwordx4 v[2:3], off
	v_lshl_add_u64 v[2:3], v[8:9], 0, s[10:11]
	s_mov_b32 m0, s48
	s_addc_u32 s15, s29, 0
	global_load_lds_dwordx4 v[2:3], off
	v_lshl_add_u64 v[2:3], s[14:15], 0, v[132:133]
	s_add_i32 m0, s42, 0x1c000
	v_lshl_add_u64 v[2:3], v[2:3], 0, v[130:131]
	global_load_lds_dwordx4 v[2:3], off
	v_lshl_add_u64 v[2:3], s[14:15], 0, v[134:135]
	v_lshl_add_u64 v[2:3], v[2:3], 0, v[130:131]
	s_add_i32 m0, s42, 0x1e000
	v_and_b32_e32 v189, 15, v0
	global_load_lds_dwordx4 v[2:3], off
	v_and_b32_e32 v2, 48, v0
	v_lshlrev_b32_e32 v186, 2, v0
	v_lshl_or_b32 v3, v189, 6, v2
	v_and_b32_e32 v4, 32, v186
	s_sext_i32_i8 s49, s12
	v_bitop3_b32 v6, v3, s13, v4 bitop3:0xde
	v_lshlrev_b32_e32 v3, 6, v0
	s_movk_i32 s12, 0x3c0
	v_and_or_b32 v2, v3, s12, v2
	v_bitop3_b32 v149, s16, v2, v4 bitop3:0xf6
	v_add_u32_e32 v2, v10, v11
	v_mov_b32_e32 v3, v133
	s_mov_b64 s[14:15], 0x160080
	s_cmpk_lt_u32 s3, 0x100
	v_lshl_add_u64 v[4:5], v[136:137], 0, v[2:3]
	s_waitcnt vmcnt(6)
	s_cselect_b64 s[12:13], -1, 0
	v_lshl_add_u64 v[140:141], v[4:5], 0, s[14:15]
	v_lshl_add_u64 v[2:3], v[138:139], 0, v[2:3]
	v_mov_b32_e32 v4, v133
	v_mov_b32_e32 v5, v133
	s_add_i32 s50, 0, 0x10000
	s_add_i32 s51, 0, 0x14000
	v_lshl_add_u64 v[142:143], v[2:3], 0, s[14:15]
	v_mov_b32_e32 v2, v133
	v_mov_b32_e32 v3, v133
	v_add_u32_e32 v150, 0, v6
	s_add_i32 s54, s50, s35
	s_add_i32 s56, s51, s35
	s_add_i32 s58, 0, 0x18000
	v_mov_b64_e32 v[8:9], v[4:5]
	v_mov_b64_e32 v[20:21], v[4:5]
	v_mov_b64_e32 v[24:25], v[4:5]
	v_mov_b64_e32 v[36:37], v[4:5]
	v_mov_b64_e32 v[40:41], v[4:5]
	v_mov_b64_e32 v[52:53], v[4:5]
	v_mov_b64_e32 v[56:57], v[4:5]
	v_mov_b64_e32 v[12:13], v[4:5]
	v_mov_b64_e32 v[16:17], v[4:5]
	v_mov_b64_e32 v[28:29], v[4:5]
	v_mov_b64_e32 v[32:33], v[4:5]
	v_mov_b64_e32 v[44:45], v[4:5]
	v_mov_b64_e32 v[48:49], v[4:5]
	v_mov_b64_e32 v[60:61], v[4:5]
	v_mov_b64_e32 v[64:65], v[4:5]
	v_mov_b64_e32 v[68:69], v[4:5]
	v_mov_b64_e32 v[72:73], v[4:5]
	v_mov_b64_e32 v[84:85], v[4:5]
	v_mov_b64_e32 v[88:89], v[4:5]
	v_mov_b64_e32 v[100:101], v[4:5]
	v_mov_b64_e32 v[104:105], v[4:5]
	v_mov_b64_e32 v[116:117], v[4:5]
	v_mov_b64_e32 v[120:121], v[4:5]
	v_mov_b64_e32 v[76:77], v[4:5]
	v_mov_b64_e32 v[80:81], v[4:5]
	v_mov_b64_e32 v[92:93], v[4:5]
	v_mov_b64_e32 v[96:97], v[4:5]
	v_mov_b64_e32 v[108:109], v[4:5]
	v_mov_b64_e32 v[112:113], v[4:5]
	v_mov_b64_e32 v[124:125], v[4:5]
	v_mov_b64_e32 v[128:129], v[4:5]
	v_or_b32_e32 v188, s46, v189
	s_mov_b32 s64, 0
	s_add_i32 s52, s42, 0xc000
	s_add_i32 s53, s42, 0xe000
	s_add_i32 s55, s54, 0x2000
	s_add_i32 s57, s56, 0x2000
	s_add_i32 s59, 0, 0x1c000
	s_add_i32 s60, s58, s35
	v_mov_b64_e32 v[6:7], v[2:3]
	v_mov_b64_e32 v[18:19], v[2:3]
	v_mov_b64_e32 v[22:23], v[2:3]
	v_mov_b64_e32 v[34:35], v[2:3]
	v_mov_b64_e32 v[38:39], v[2:3]
	v_mov_b64_e32 v[50:51], v[2:3]
	v_mov_b64_e32 v[54:55], v[2:3]
	v_mov_b64_e32 v[10:11], v[2:3]
	v_mov_b64_e32 v[14:15], v[2:3]
	v_mov_b64_e32 v[26:27], v[2:3]
	v_mov_b64_e32 v[30:31], v[2:3]
	v_mov_b64_e32 v[42:43], v[2:3]
	v_mov_b64_e32 v[46:47], v[2:3]
	v_mov_b64_e32 v[58:59], v[2:3]
	v_mov_b64_e32 v[62:63], v[2:3]
	v_mov_b64_e32 v[66:67], v[2:3]
	v_mov_b64_e32 v[70:71], v[2:3]
	v_mov_b64_e32 v[82:83], v[2:3]
	v_mov_b64_e32 v[86:87], v[2:3]
	v_mov_b64_e32 v[98:99], v[2:3]
	v_mov_b64_e32 v[102:103], v[2:3]
	v_mov_b64_e32 v[114:115], v[2:3]
	v_mov_b64_e32 v[118:119], v[2:3]
	v_mov_b64_e32 v[74:75], v[2:3]
	v_mov_b64_e32 v[78:79], v[2:3]
	v_mov_b64_e32 v[90:91], v[2:3]
	v_mov_b64_e32 v[94:95], v[2:3]
	v_mov_b64_e32 v[106:107], v[2:3]
	v_mov_b64_e32 v[110:111], v[2:3]
	v_mov_b64_e32 v[122:123], v[2:3]
	v_mov_b64_e32 v[126:127], v[2:3]
	s_mov_b64 s[18:19], s[28:29]
	s_mov_b64 s[16:17], s[20:21]
	v_add_u32_e32 v132, v132, v130
	v_add_u32_e32 v134, v134, v130
	v_add_u32_e32 v136, v136, v130
	v_add_u32_e32 v138, v138, v130
	s_barrier

; #define PG8_STAGE(bufoff, gbase, RR, ld) do { _Pragma("unroll") for (int _i = 0; _i < 2; ++_i) \
;         __builtin_amdgcn_global_load_lds((const unsigned*)((const char*)(gbase) + (RR)[_i] * (ld) + C2[_i]), (LAS unsigned*)(lds + (bufoff) + ldsw + _i * 8192), 16, 0, 0); } while (0)
; #define PG8_LDA(dst, b, h) do { _Pragma("unroll") for (int m = 0; m < 4; ++m) _Pragma("unroll") for (int k = 0; k < 2; ++k) dst[m][k] = *(const LAS bf16x8*)(lds + PG8_SA(b, h) + aoff + m * 2048 + k * 1024); } while (0)
; #define PG8_LDB(dst, b, h) do { _Pragma("unroll") for (int n = 0; n < 2; ++n) _Pragma("unroll") for (int k = 0; k < 2; ++k) dst[n][k] = *(const LAS bf16x8*)(lds + PG8_SB(b, h) + boff + n * 2048 + k * 1024); } while (0)
; #define PG8_MMA(ai, bj, At, Bt) do { __builtin_amdgcn_s_setprio(1); _Pragma("unroll") for (int m = 0; m < 4; ++m) _Pragma("unroll") for (int n = 0; n < 2; ++n) _Pragma("unroll") for (int k = 0; k < 2; ++k) \
;         acc[ai][bj][m][n] = __builtin_amdgcn_mfma_f32_16x16x32_bf16(Bt[n][k], At[m][k], acc[ai][bj][m][n], 0, 0, 0); __builtin_amdgcn_s_setprio(0); } while (0)
; template <class Sched, class Epi>
; __device__ __forceinline__ void gemm_run(LAS unsigned char* lds, const Sched& S, const Epi& E) {
;     ...
;         const bool has_next = S.next(ui + 1, nxt);
;         const char* nA = has_next ? nxt.A : cA; const char* nB = has_next ? nxt.B : cB; const unsigned nlda = has_next ? nxt.lda : lda, nldb = has_next ? nxt.ldb : ldb;
;         const int nt = cur.nt;
;         for (int t = 0; t < nt; t += 2) {
;             const bool last = (t == nt - 2);
;             const char* a1 = cA + (size_t)(t + 1) * kstep;
;             const char* a2 = last ? nA : cA + (size_t)(t + 2) * kstep; const char* b2 = last ? nB : cB + (size_t)(t + 2) * kstep;
;             const unsigned la2 = last ? nlda : lda, lb2 = last ? nldb : ldb;
;             const char* a3 = a2 + kstep; const char* b3 = b2 + kstep;
;             PG8_LDB(B0, 0, 0); PG8_LDB(B1, 0, 1); PG8_SCHED; PG8_LDA(At, 0, 0); PG8_STAGE(PG8_SA(1, 1), a1 + (size_t)HALF * lda, RA, lda);
;             PG8_WAIT_V(8); PG8_WAIT_L(0); PG8_BAR; PG8_MMA(0, 0, At, B0); PG8_MMA(0, 1, At, B1); PG8_BAR; PG8_SCHED;
;             PG8_LDA(At, 0, 1); PG8_STAGE(PG8_SB(0, 0), b2, RB, lb2); PG8_STAGE(PG8_SB(0, 1), b2 + (size_t)HALF * lb2, RB, lb2); PG8_STAGE(PG8_SA(0, 0), a2, RA, la2);
.LBB0_1067:
	s_add_u32 s65, s28, 0x100
	s_addc_u32 s66, s29, 0
	s_mov_b32 s67, -2
	s_mov_b64 s[28:29], 0
	.p2align 6
.LBB0_1068:
	v_add_u32_e32 v151, s50, v149
	ds_read_b128 v[152:155], v151
	ds_read_b128 v[156:159], v151 offset:1024
	ds_read_b128 v[160:163], v151 offset:2048
	ds_read_b128 v[164:167], v151 offset:3072
	v_add_u32_e32 v151, s51, v149
	s_add_u32 s30, s20, s28
	ds_read_b128 v[168:171], v151
	ds_read_b128 v[172:175], v151 offset:1024
	ds_read_b128 v[176:179], v151 offset:2048
	ds_read_b128 v[180:183], v151 offset:3072
	s_addc_u32 s31, s21, s29
	s_mov_b32 s98, s30
	s_mov_b32 s99, s31
	s_add_u32 s30, s30, 0x100
	s_addc_u32 s31, s31, 0
	s_add_u32 s68, s65, s28
	s_addc_u32 s69, s66, s29
	s_cmpk_eq_i32 s28, 0x2b00
	s_cselect_b32 s37, s17, s31
	s_cselect_b32 s36, s16, s30
	s_cselect_b32 s31, s19, s69
	s_cselect_b32 s30, s18, s68
	s_mov_b64 s[100:101], s[36:37]
	s_mov_b32 m0, s52
	ds_read_b128 v[190:193], v150
	ds_read_b128 v[194:197], v150 offset:1024
	ds_read_b128 v[198:201], v150 offset:2048
	ds_read_b128 v[202:205], v150 offset:3072
	ds_read_b128 v[206:209], v150 offset:4096
	ds_read_b128 v[210:213], v150 offset:5120
	ds_read_b128 v[214:217], v150 offset:6144
	ds_read_b128 v[218:221], v150 offset:7168
	global_load_lds_dwordx4 v140, s[98:99]
	s_mov_b32 m0, s53
	s_nop 0
	global_load_lds_dwordx4 v142, s[98:99]
	s_waitcnt vmcnt(8)
	s_waitcnt lgkmcnt(0)
	s_barrier
	s_waitcnt lgkmcnt(0)
	v_mfma_f32_16x16x32_bf16 v[126:129], v[152:155], v[190:193], v[126:129]
	v_mfma_f32_16x16x32_bf16 v[122:125], v[160:163], v[190:193], v[122:125]
	v_mfma_f32_16x16x32_bf16 v[110:113], v[152:155], v[198:201], v[110:113]
	v_mfma_f32_16x16x32_bf16 v[106:109], v[160:163], v[198:201], v[106:109]
	v_mfma_f32_16x16x32_bf16 v[94:97], v[152:155], v[206:209], v[94:97]
	v_mfma_f32_16x16x32_bf16 v[90:93], v[160:163], v[206:209], v[90:93]
	v_mfma_f32_16x16x32_bf16 v[78:81], v[152:155], v[214:217], v[78:81]
	v_mfma_f32_16x16x32_bf16 v[74:77], v[160:163], v[214:217], v[74:77]
	v_mfma_f32_16x16x32_bf16 v[126:129], v[156:159], v[194:197], v[126:129]
	v_mfma_f32_16x16x32_bf16 v[122:125], v[164:167], v[194:197], v[122:125]
	v_mfma_f32_16x16x32_bf16 v[110:113], v[156:159], v[202:205], v[110:113]
	v_mfma_f32_16x16x32_bf16 v[106:109], v[164:167], v[202:205], v[106:109]
	v_mfma_f32_16x16x32_bf16 v[94:97], v[156:159], v[210:213], v[94:97]
	v_mfma_f32_16x16x32_bf16 v[90:93], v[164:167], v[210:213], v[90:93]
	v_mfma_f32_16x16x32_bf16 v[78:81], v[156:159], v[218:221], v[78:81]
	v_mfma_f32_16x16x32_bf16 v[74:77], v[164:167], v[218:221], v[74:77]
	v_mfma_f32_16x16x32_bf16 v[118:121], v[168:171], v[190:193], v[118:121]
	v_mfma_f32_16x16x32_bf16 v[114:117], v[176:179], v[190:193], v[114:117]
	v_mfma_f32_16x16x32_bf16 v[102:105], v[168:171], v[198:201], v[102:105]
	v_mfma_f32_16x16x32_bf16 v[98:101], v[176:179], v[198:201], v[98:101]
	v_mfma_f32_16x16x32_bf16 v[86:89], v[168:171], v[206:209], v[86:89]
	v_mfma_f32_16x16x32_bf16 v[82:85], v[176:179], v[206:209], v[82:85]
	v_mfma_f32_16x16x32_bf16 v[70:73], v[168:171], v[214:217], v[70:73]
	v_mfma_f32_16x16x32_bf16 v[66:69], v[176:179], v[214:217], v[66:69]
	v_mfma_f32_16x16x32_bf16 v[118:121], v[172:175], v[194:197], v[118:121]
	v_mfma_f32_16x16x32_bf16 v[114:117], v[180:183], v[194:197], v[114:117]
	v_mfma_f32_16x16x32_bf16 v[102:105], v[172:175], v[202:205], v[102:105]
	v_mfma_f32_16x16x32_bf16 v[98:101], v[180:183], v[202:205], v[98:101]
	v_mfma_f32_16x16x32_bf16 v[86:89], v[172:175], v[210:213], v[86:89]
	v_mfma_f32_16x16x32_bf16 v[82:85], v[180:183], v[210:213], v[82:85]
	v_mfma_f32_16x16x32_bf16 v[70:73], v[172:175], v[218:221], v[70:73]
	v_mfma_f32_16x16x32_bf16 v[66:69], v[180:183], v[218:221], v[66:69]
	s_barrier
	s_add_u32 s68, s30, 0x160000
	s_mov_b32 m0, s54
	s_addc_u32 s69, s31, 0
	ds_read_b128 v[190:193], v150 offset:16384
	ds_read_b128 v[194:197], v150 offset:17408
	ds_read_b128 v[198:201], v150 offset:18432
	ds_read_b128 v[202:205], v150 offset:19456
	ds_read_b128 v[206:209], v150 offset:20480
	ds_read_b128 v[210:213], v150 offset:21504
	ds_read_b128 v[214:217], v150 offset:22528
	ds_read_b128 v[218:221], v150 offset:23552
	global_load_lds_dwordx4 v132, s[30:31]
	s_mov_b32 m0, s55
	s_nop 0
	global_load_lds_dwordx4 v134, s[30:31]
	s_mov_b32 m0, s56
	s_nop 0
	global_load_lds_dwordx4 v132, s[68:69]
	s_mov_b32 m0, s57
	s_nop 0
	global_load_lds_dwordx4 v134, s[68:69]
	s_mov_b32 m0, s42
	s_nop 0
	global_load_lds_dwordx4 v136, s[36:37]
	s_mov_b32 m0, s43
	s_nop 0
	global_load_lds_dwordx4 v138, s[36:37]
	s_waitcnt vmcnt(8)
	s_waitcnt lgkmcnt(0)
	s_barrier
; #define PG8_STAGE(bufoff, gbase, RR, ld) do { _Pragma("unroll") for (int _i = 0; _i < 2; ++_i) \
;         __builtin_amdgcn_global_load_lds((const unsigned*)((const char*)(gbase) + (RR)[_i] * (ld) + C2[_i]), (LAS unsigned*)(lds + (bufoff) + ldsw + _i * 8192), 16, 0, 0); } while (0)
; #define PG8_LDA(dst, b, h) do { _Pragma("unroll") for (int m = 0; m < 4; ++m) _Pragma("unroll") for (int k = 0; k < 2; ++k) dst[m][k] = *(const LAS bf16x8*)(lds + PG8_SA(b, h) + aoff + m * 2048 + k * 1024); } while (0)
; #define PG8_LDB(dst, b, h) do { _Pragma("unroll") for (int n = 0; n < 2; ++n) _Pragma("unroll") for (int k = 0; k < 2; ++k) dst[n][k] = *(const LAS bf16x8*)(lds + PG8_SB(b, h) + boff + n * 2048 + k * 1024); } while (0)
; #define PG8_MMA(ai, bj, At, Bt) do { __builtin_amdgcn_s_setprio(1); _Pragma("unroll") for (int m = 0; m < 4; ++m) _Pragma("unroll") for (int n = 0; n < 2; ++n) _Pragma("unroll") for (int k = 0; k < 2; ++k) \
;         acc[ai][bj][m][n] = __builtin_amdgcn_mfma_f32_16x16x32_bf16(Bt[n][k], At[m][k], acc[ai][bj][m][n], 0, 0, 0); __builtin_amdgcn_s_setprio(0); } while (0)
; #define PG8_WAIT_V(n) asm volatile("s_waitcnt vmcnt(" #n ")" ::: "memory")
; #define PG8_WAIT_L(n) asm volatile("s_waitcnt lgkmcnt(" #n ")" ::: "memory")
; #define PG8_BAR __builtin_amdgcn_s_barrier()
; #define PG8_SCHED __builtin_amdgcn_sched_barrier(0)
; template <class Sched, class Epi>
; __device__ __forceinline__ void gemm_run(LAS unsigned char* lds, const Sched& S, const Epi& E) {
;     ...
;             PG8_WAIT_V(8); PG8_WAIT_L(0); PG8_BAR; PG8_MMA(1, 0, At, B0); PG8_MMA(1, 1, At, B1); PG8_BAR; PG8_SCHED;
;             PG8_LDB(B0, 1, 0); PG8_LDB(B1, 1, 1); PG8_SCHED; PG8_LDA(At, 1, 0); PG8_STAGE(PG8_SA(0, 1), a2 + (size_t)HALF * la2, RA, la2);
;             PG8_WAIT_V(8); PG8_WAIT_L(0); PG8_BAR; PG8_MMA(0, 0, At, B0); PG8_MMA(0, 1, At, B1); PG8_BAR; PG8_SCHED;
	s_waitcnt lgkmcnt(0)
	v_mfma_f32_16x16x32_bf16 v[62:65], v[152:155], v[190:193], v[62:65]
	v_mfma_f32_16x16x32_bf16 v[58:61], v[160:163], v[190:193], v[58:61]
	v_mfma_f32_16x16x32_bf16 v[46:49], v[152:155], v[198:201], v[46:49]
	v_mfma_f32_16x16x32_bf16 v[42:45], v[160:163], v[198:201], v[42:45]
	v_mfma_f32_16x16x32_bf16 v[30:33], v[152:155], v[206:209], v[30:33]
	v_mfma_f32_16x16x32_bf16 v[26:29], v[160:163], v[206:209], v[26:29]
	v_mfma_f32_16x16x32_bf16 v[14:17], v[152:155], v[214:217], v[14:17]
	v_mfma_f32_16x16x32_bf16 v[10:13], v[160:163], v[214:217], v[10:13]
	v_mfma_f32_16x16x32_bf16 v[62:65], v[156:159], v[194:197], v[62:65]
	v_mfma_f32_16x16x32_bf16 v[58:61], v[164:167], v[194:197], v[58:61]
	v_mfma_f32_16x16x32_bf16 v[46:49], v[156:159], v[202:205], v[46:49]
	v_mfma_f32_16x16x32_bf16 v[42:45], v[164:167], v[202:205], v[42:45]
	v_mfma_f32_16x16x32_bf16 v[30:33], v[156:159], v[210:213], v[30:33]
	v_mfma_f32_16x16x32_bf16 v[26:29], v[164:167], v[210:213], v[26:29]
	v_mfma_f32_16x16x32_bf16 v[14:17], v[156:159], v[218:221], v[14:17]
	v_mfma_f32_16x16x32_bf16 v[10:13], v[164:167], v[218:221], v[10:13]
	v_mfma_f32_16x16x32_bf16 v[54:57], v[168:171], v[190:193], v[54:57]
	v_mfma_f32_16x16x32_bf16 v[50:53], v[176:179], v[190:193], v[50:53]
	v_mfma_f32_16x16x32_bf16 v[38:41], v[168:171], v[198:201], v[38:41]
	v_mfma_f32_16x16x32_bf16 v[34:37], v[176:179], v[198:201], v[34:37]
	v_mfma_f32_16x16x32_bf16 v[22:25], v[168:171], v[206:209], v[22:25]
	v_mfma_f32_16x16x32_bf16 v[18:21], v[176:179], v[206:209], v[18:21]
	v_mfma_f32_16x16x32_bf16 v[6:9], v[168:171], v[214:217], v[6:9]
	v_mfma_f32_16x16x32_bf16 v[2:5], v[176:179], v[214:217], v[2:5]
	v_mfma_f32_16x16x32_bf16 v[54:57], v[172:175], v[194:197], v[54:57]
	v_mfma_f32_16x16x32_bf16 v[50:53], v[180:183], v[194:197], v[50:53]
	v_mfma_f32_16x16x32_bf16 v[38:41], v[172:175], v[202:205], v[38:41]
	v_mfma_f32_16x16x32_bf16 v[34:37], v[180:183], v[202:205], v[34:37]
	v_mfma_f32_16x16x32_bf16 v[22:25], v[172:175], v[210:213], v[22:25]
	v_mfma_f32_16x16x32_bf16 v[18:21], v[180:183], v[210:213], v[18:21]
	v_mfma_f32_16x16x32_bf16 v[6:9], v[172:175], v[218:221], v[6:9]
	v_mfma_f32_16x16x32_bf16 v[2:5], v[180:183], v[218:221], v[2:5]
	s_barrier
	v_add_u32_e32 v151, s58, v149
	ds_read_b128 v[152:155], v151
	ds_read_b128 v[156:159], v151 offset:1024
	ds_read_b128 v[160:163], v151 offset:2048
	ds_read_b128 v[164:167], v151 offset:3072
	v_add_u32_e32 v151, s59, v149
	ds_read_b128 v[168:171], v151
	ds_read_b128 v[172:175], v151 offset:1024
	ds_read_b128 v[176:179], v151 offset:2048
	ds_read_b128 v[180:183], v151 offset:3072
	s_add_u32 s36, s36, 0x160000
	s_addc_u32 s37, s37, 0
	s_mov_b32 m0, s44
	ds_read_b128 v[190:193], v150 offset:32768
	ds_read_b128 v[194:197], v150 offset:33792
	ds_read_b128 v[198:201], v150 offset:34816
	ds_read_b128 v[202:205], v150 offset:35840
	ds_read_b128 v[206:209], v150 offset:36864
	ds_read_b128 v[210:213], v150 offset:37888
	ds_read_b128 v[214:217], v150 offset:38912
	ds_read_b128 v[218:221], v150 offset:39936
	global_load_lds_dwordx4 v136, s[36:37]
	s_mov_b32 m0, s45
	s_nop 0
	global_load_lds_dwordx4 v138, s[36:37]
	s_waitcnt vmcnt(8)
	s_waitcnt lgkmcnt(0)
	s_barrier
	s_waitcnt lgkmcnt(0)
	v_mfma_f32_16x16x32_bf16 v[126:129], v[152:155], v[190:193], v[126:129]
	v_mfma_f32_16x16x32_bf16 v[122:125], v[160:163], v[190:193], v[122:125]
	v_mfma_f32_16x16x32_bf16 v[110:113], v[152:155], v[198:201], v[110:113]
	v_mfma_f32_16x16x32_bf16 v[106:109], v[160:163], v[198:201], v[106:109]
	v_mfma_f32_16x16x32_bf16 v[94:97], v[152:155], v[206:209], v[94:97]
	v_mfma_f32_16x16x32_bf16 v[90:93], v[160:163], v[206:209], v[90:93]
	v_mfma_f32_16x16x32_bf16 v[78:81], v[152:155], v[214:217], v[78:81]
	v_mfma_f32_16x16x32_bf16 v[74:77], v[160:163], v[214:217], v[74:77]
	v_mfma_f32_16x16x32_bf16 v[126:129], v[156:159], v[194:197], v[126:129]
	v_mfma_f32_16x16x32_bf16 v[122:125], v[164:167], v[194:197], v[122:125]
	v_mfma_f32_16x16x32_bf16 v[110:113], v[156:159], v[202:205], v[110:113]
	v_mfma_f32_16x16x32_bf16 v[106:109], v[164:167], v[202:205], v[106:109]
	v_mfma_f32_16x16x32_bf16 v[94:97], v[156:159], v[210:213], v[94:97]
	v_mfma_f32_16x16x32_bf16 v[90:93], v[164:167], v[210:213], v[90:93]
	v_mfma_f32_16x16x32_bf16 v[78:81], v[156:159], v[218:221], v[78:81]
	v_mfma_f32_16x16x32_bf16 v[74:77], v[164:167], v[218:221], v[74:77]
	v_mfma_f32_16x16x32_bf16 v[118:121], v[168:171], v[190:193], v[118:121]
	v_mfma_f32_16x16x32_bf16 v[114:117], v[176:179], v[190:193], v[114:117]
	v_mfma_f32_16x16x32_bf16 v[102:105], v[168:171], v[198:201], v[102:105]
	v_mfma_f32_16x16x32_bf16 v[98:101], v[176:179], v[198:201], v[98:101]
	v_mfma_f32_16x16x32_bf16 v[86:89], v[168:171], v[206:209], v[86:89]
	v_mfma_f32_16x16x32_bf16 v[82:85], v[176:179], v[206:209], v[82:85]
	v_mfma_f32_16x16x32_bf16 v[70:73], v[168:171], v[214:217], v[70:73]
	v_mfma_f32_16x16x32_bf16 v[66:69], v[176:179], v[214:217], v[66:69]
	v_mfma_f32_16x16x32_bf16 v[118:121], v[172:175], v[194:197], v[118:121]
	v_mfma_f32_16x16x32_bf16 v[114:117], v[180:183], v[194:197], v[114:117]
	v_mfma_f32_16x16x32_bf16 v[102:105], v[172:175], v[202:205], v[102:105]
	v_mfma_f32_16x16x32_bf16 v[98:101], v[180:183], v[202:205], v[98:101]
	v_mfma_f32_16x16x32_bf16 v[86:89], v[172:175], v[210:213], v[86:89]
	v_mfma_f32_16x16x32_bf16 v[82:85], v[180:183], v[210:213], v[82:85]
	v_mfma_f32_16x16x32_bf16 v[70:73], v[172:175], v[218:221], v[70:73]
	v_mfma_f32_16x16x32_bf16 v[66:69], v[180:183], v[218:221], v[66:69]
	s_barrier
; #define PG8_STAGE(bufoff, gbase, RR, ld) do { _Pragma("unroll") for (int _i = 0; _i < 2; ++_i) \
;         __builtin_amdgcn_global_load_lds((const unsigned*)((const char*)(gbase) + (RR)[_i] * (ld) + C2[_i]), (LAS unsigned*)(lds + (bufoff) + ldsw + _i * 8192), 16, 0, 0); } while (0)
; #define PG8_LDA(dst, b, h) do { _Pragma("unroll") for (int m = 0; m < 4; ++m) _Pragma("unroll") for (int k = 0; k < 2; ++k) dst[m][k] = *(const LAS bf16x8*)(lds + PG8_SA(b, h) + aoff + m * 2048 + k * 1024); } while (0)
; #define PG8_MMA(ai, bj, At, Bt) do { __builtin_amdgcn_s_setprio(1); _Pragma("unroll") for (int m = 0; m < 4; ++m) _Pragma("unroll") for (int n = 0; n < 2; ++n) _Pragma("unroll") for (int k = 0; k < 2; ++k) \
;         acc[ai][bj][m][n] = __builtin_amdgcn_mfma_f32_16x16x32_bf16(Bt[n][k], At[m][k], acc[ai][bj][m][n], 0, 0, 0); __builtin_amdgcn_s_setprio(0); } while (0)
; #define PG8_WAIT_V(n) asm volatile("s_waitcnt vmcnt(" #n ")" ::: "memory")
; #define PG8_WAIT_L(n) asm volatile("s_waitcnt lgkmcnt(" #n ")" ::: "memory")
; #define PG8_BAR __builtin_amdgcn_s_barrier()
; #define PG8_SCHED __builtin_amdgcn_sched_barrier(0)
; template <class Sched, class Epi>
; __device__ __forceinline__ void gemm_run(LAS unsigned char* lds, const Sched& S, const Epi& E) {
;     ...
;             PG8_LDA(At, 1, 1); PG8_STAGE(PG8_SB(1, 0), b3, RB, lb2); PG8_STAGE(PG8_SB(1, 1), b3 + (size_t)HALF * lb2, RB, lb2); PG8_STAGE(PG8_SA(1, 0), a3, RA, la2);
;             PG8_WAIT_V(8); PG8_WAIT_L(0); PG8_BAR; PG8_MMA(1, 0, At, B0); PG8_MMA(1, 1, At, B1); PG8_BAR; PG8_SCHED;
;         }
	s_mov_b32 m0, s60
	ds_read_b128 v[190:193], v150 offset:49152
	ds_read_b128 v[194:197], v150 offset:50176
	ds_read_b128 v[198:201], v150 offset:51200
	ds_read_b128 v[202:205], v150 offset:52224
	ds_read_b128 v[206:209], v150 offset:53248
	ds_read_b128 v[210:213], v150 offset:54272
	ds_read_b128 v[214:217], v150 offset:55296
	ds_read_b128 v[218:221], v150 offset:56320
	s_add_u32 s98, s30, 0x80
	s_addc_u32 s99, s31, 0
	global_load_lds_dwordx4 v132, s[98:99]
	s_add_i32 m0, s60, 0x2000
	s_nop 0
	global_load_lds_dwordx4 v134, s[98:99]
	s_add_u32 s30, s30, 0x160080
	s_addc_u32 s31, s31, 0
	s_add_i32 s36, s59, s35
	s_mov_b32 m0, s36
	s_nop 0
	global_load_lds_dwordx4 v132, s[30:31]
	s_add_i32 m0, s36, 0x2000
	s_nop 0
	global_load_lds_dwordx4 v134, s[30:31]
	s_mov_b32 m0, s47
	s_nop 0
	s_add_u32 s100, s100, 0x80
	s_addc_u32 s101, s101, 0
	global_load_lds_dwordx4 v136, s[100:101]
	s_mov_b32 m0, s48
	s_nop 0
	global_load_lds_dwordx4 v138, s[100:101]
	s_waitcnt vmcnt(8)
	s_waitcnt lgkmcnt(0)
	s_barrier
	s_waitcnt lgkmcnt(0)
	v_mfma_f32_16x16x32_bf16 v[62:65], v[152:155], v[190:193], v[62:65]
	v_mfma_f32_16x16x32_bf16 v[58:61], v[160:163], v[190:193], v[58:61]
	v_mfma_f32_16x16x32_bf16 v[46:49], v[152:155], v[198:201], v[46:49]
	v_mfma_f32_16x16x32_bf16 v[42:45], v[160:163], v[198:201], v[42:45]
	v_mfma_f32_16x16x32_bf16 v[30:33], v[152:155], v[206:209], v[30:33]
	v_mfma_f32_16x16x32_bf16 v[26:29], v[160:163], v[206:209], v[26:29]
	v_mfma_f32_16x16x32_bf16 v[14:17], v[152:155], v[214:217], v[14:17]
	v_mfma_f32_16x16x32_bf16 v[10:13], v[160:163], v[214:217], v[10:13]
	v_mfma_f32_16x16x32_bf16 v[62:65], v[156:159], v[194:197], v[62:65]
	v_mfma_f32_16x16x32_bf16 v[58:61], v[164:167], v[194:197], v[58:61]
	v_mfma_f32_16x16x32_bf16 v[46:49], v[156:159], v[202:205], v[46:49]
	v_mfma_f32_16x16x32_bf16 v[42:45], v[164:167], v[202:205], v[42:45]
	v_mfma_f32_16x16x32_bf16 v[30:33], v[156:159], v[210:213], v[30:33]
	v_mfma_f32_16x16x32_bf16 v[26:29], v[164:167], v[210:213], v[26:29]
	v_mfma_f32_16x16x32_bf16 v[14:17], v[156:159], v[218:221], v[14:17]
	v_mfma_f32_16x16x32_bf16 v[10:13], v[164:167], v[218:221], v[10:13]
	v_mfma_f32_16x16x32_bf16 v[54:57], v[168:171], v[190:193], v[54:57]
	v_mfma_f32_16x16x32_bf16 v[50:53], v[176:179], v[190:193], v[50:53]
	v_mfma_f32_16x16x32_bf16 v[38:41], v[168:171], v[198:201], v[38:41]
	v_mfma_f32_16x16x32_bf16 v[34:37], v[176:179], v[198:201], v[34:37]
	v_mfma_f32_16x16x32_bf16 v[22:25], v[168:171], v[206:209], v[22:25]
	v_mfma_f32_16x16x32_bf16 v[18:21], v[176:179], v[206:209], v[18:21]
	v_mfma_f32_16x16x32_bf16 v[6:9], v[168:171], v[214:217], v[6:9]
	v_mfma_f32_16x16x32_bf16 v[2:5], v[176:179], v[214:217], v[2:5]
	v_mfma_f32_16x16x32_bf16 v[54:57], v[172:175], v[194:197], v[54:57]
	v_mfma_f32_16x16x32_bf16 v[50:53], v[180:183], v[194:197], v[50:53]
	v_mfma_f32_16x16x32_bf16 v[38:41], v[172:175], v[202:205], v[38:41]
	v_mfma_f32_16x16x32_bf16 v[34:37], v[180:183], v[202:205], v[34:37]
	v_mfma_f32_16x16x32_bf16 v[22:25], v[172:175], v[210:213], v[22:25]
	v_mfma_f32_16x16x32_bf16 v[18:21], v[180:183], v[210:213], v[18:21]
	v_mfma_f32_16x16x32_bf16 v[6:9], v[172:175], v[218:221], v[6:9]
	v_mfma_f32_16x16x32_bf16 v[2:5], v[180:183], v[218:221], v[2:5]
	s_barrier
	s_add_i32 s67, s67, 2
	s_add_u32 s28, s28, 0x100
	s_addc_u32 s29, s29, 0
	s_cmpk_gt_u32 s67, 0x55
	s_cbranch_scc0 .LBB0_1068
	s_and_b64 vcc, exec, s[12:13]
	s_cbranch_vccz .LBB0_1071
	s_barrier

; #define PG8_STAGE(bufoff, gbase, RR, ld) do { _Pragma("unroll") for (int _i = 0; _i < 2; ++_i) \
;         __builtin_amdgcn_global_load_lds((const unsigned*)((const char*)(gbase) + (RR)[_i] * (ld) + C2[_i]), (LAS unsigned*)(lds + (bufoff) + ldsw + _i * 8192), 16, 0, 0); } while (0)
; #define PG8_WAIT_V(n) asm volatile("s_waitcnt vmcnt(" #n ")" ::: "memory")
; #define PG8_BAR __builtin_amdgcn_s_barrier()
; template <class Sched, class Epi>
; __device__ __forceinline__ void gemm_run(LAS unsigned char* lds, const Sched& S, const Epi& E) {
;     const int tid = threadIdx.x, wid = __builtin_amdgcn_readfirstlane(tid >> 6), lane = tid & 63, wr = wid >> 2, wc = wid & 3, fr = lane & 15, fq = lane >> 4;
;     unsigned RA[2], RB[2], C2[2];
; #pragma unroll
;     for (int i = 0; i < 2; ++i) { int R, C; stage_rc(tid * 16 + i * 8192, R, C); RA[i] = (unsigned)R; RB[i] = (unsigned)((R & ~31) + perm32(R & 31)); C2[i] = (unsigned)(C * 2); }
;     const unsigned ldsw = (unsigned)wid * 1024u;
;     const int aoff = lds_byte(wr * 64 + fr, fq * 8), boff = lds_byte(wc * 32 + fr, fq * 8);
;     ...
;     Unit cur, nxt; int ui = 0;
;     if (!S.next(0, cur)) return;
;     f32x4 acc[2][2][4][2];
; #pragma unroll
;     for (int a = 0; a < 2; ++a)
; #pragma unroll
;         for (int b = 0; b < 2; ++b)
; #pragma unroll
;             for (int m = 0; m < 4; ++m)
; #pragma unroll
;                 for (int n = 0; n < 2; ++n) acc[a][b][m][n] = (f32x4){0.f, 0.f, 0.f, 0.f};
;     bf16x8 At[4][2], B0[2][2], B1[2][2];
;     const char* cA = cur.A; const char* cB = cur.B; unsigned lda = cur.lda, ldb = cur.ldb;
;     constexpr unsigned kstep = BK * 2;
;     PG8_STAGE(PG8_SB(0, 0), cB, RB, ldb); PG8_STAGE(PG8_SB(0, 1), cB + (size_t)HALF * ldb, RB, ldb); PG8_STAGE(PG8_SA(0, 0), cA, RA, lda); PG8_STAGE(PG8_SA(0, 1), cA + (size_t)HALF * lda, RA, lda);
;     if (wr == 1) PG8_BAR;
;     PG8_WAIT_V(2); PG8_BAR;
;     PG8_STAGE(PG8_SB(1, 0), cB + kstep, RB, ldb); PG8_STAGE(PG8_SA(1, 0), cA + kstep, RA, lda); PG8_STAGE(PG8_SB(1, 1), cB + (size_t)HALF * ldb + kstep, RB, ldb);
;     PG8_WAIT_V(6); PG8_BAR;
.LBB0_1118:
	s_lshl_b32 s1, s1, 5
	s_mov_b64 s[10:11], 0x80
	s_and_b32 s1, s1, 0x60
	s_add_i32 m0, s33, 0x18000
	v_lshl_add_u64 v[2:3], v[2:3], 0, s[10:11]
	s_lshl_b32 s13, s0, 13
	s_lshl_b32 s16, s1, 7
	s_waitcnt vmcnt(2)
	s_barrier
	global_load_lds_dwordx4 v[2:3], off
	v_lshl_add_u64 v[2:3], v[4:5], 0, s[10:11]
	s_add_i32 m0, s33, 0x1a000
	s_add_i32 s43, s33, 0x8000
	s_add_i32 s44, s33, 0xa000
	global_load_lds_dwordx4 v[2:3], off
	v_lshl_add_u64 v[2:3], v[6:7], 0, s[10:11]
	s_mov_b32 m0, s43
	s_add_u32 s14, s30, 0x160080
	global_load_lds_dwordx4 v[2:3], off
	v_lshl_add_u64 v[2:3], v[8:9], 0, s[10:11]
	s_mov_b32 m0, s44
	s_addc_u32 s15, s31, 0
	global_load_lds_dwordx4 v[2:3], off
	v_lshl_add_u64 v[2:3], s[14:15], 0, v[132:133]
	s_add_i32 m0, s33, 0x1c000
	v_lshl_add_u64 v[2:3], v[2:3], 0, v[130:131]
	global_load_lds_dwordx4 v[2:3], off
	v_lshl_add_u64 v[2:3], s[14:15], 0, v[134:135]
	v_lshl_add_u64 v[2:3], v[2:3], 0, v[130:131]
	s_add_i32 m0, s33, 0x1e000
	v_lshlrev_b32_e32 v5, 2, v0
	global_load_lds_dwordx4 v[2:3], off
	v_bfe_u32 v3, v0, 4, 2
	v_and_b32_e32 v2, 15, v0
	v_lshlrev_b32_e32 v4, 4, v3
	v_lshl_or_b32 v1, s0, 6, v2
	v_lshl_or_b32 v2, v2, 6, v4
	v_and_b32_e32 v5, 32, v5
	s_cmpk_lt_u32 s12, 0x100
	v_bitop3_b32 v6, v2, s13, v5 bitop3:0xde
	s_cselect_b64 s[12:13], -1, 0
	s_add_u32 s45, s86, 0x2400000
	s_addc_u32 s46, s87, 0
	s_add_u32 s47, s86, 0xde00000
	v_lshlrev_b32_e32 v2, 6, v0
	s_movk_i32 s0, 0x3c0
	s_addc_u32 s48, s87, 0
	v_and_or_b32 v2, v2, s0, v4
	s_add_u32 s14, s86, 0x400000
	v_bitop3_b32 v141, s16, v2, v5 bitop3:0xf6
	v_lshl_or_b32 v140, v3, 3, s1
	v_cmp_eq_u32_e64 s[0:1], 0, v3
	s_addc_u32 s15, s87, 0
	v_add_u32_e32 v2, v10, v11
	v_mov_b32_e32 v3, v133
	s_mov_b64 s[18:19], 0x160080
	s_waitcnt vmcnt(6)
	s_add_u32 s16, s86, 0x40000
	v_lshl_add_u64 v[4:5], v[136:137], 0, v[2:3]
	v_lshl_add_u64 v[2:3], v[138:139], 0, v[2:3]
	s_addc_u32 s17, s87, 0
	v_lshl_add_u64 v[144:145], v[2:3], 0, s[18:19]
	s_add_i32 s49, 0, 0x10000
	s_add_i32 s50, 0, 0x14000
	v_mbcnt_lo_u32_b32 v2, -1, 0
	v_lshl_add_u64 v[142:143], v[4:5], 0, s[18:19]
	s_waitcnt vmcnt(0)
	v_add_u32_e32 v150, s49, v141
	v_add_u32_e32 v151, s50, v141
	v_add_u32_e32 v152, 0, v6
	v_mbcnt_hi_u32_b32 v153, -1, v2
	s_mov_b64 s[22:23], s[30:31]
	s_mov_b64 s[18:19], s[28:29]
	v_add_u32_e32 v132, v132, v130
	v_add_u32_e32 v134, v134, v130
	v_add_u32_e32 v136, v136, v130
	v_add_u32_e32 v138, v138, v130
	s_barrier
	s_branch .LBB0_1121

; #define PG8_STAGE(bufoff, gbase, RR, ld) do { _Pragma("unroll") for (int _i = 0; _i < 2; ++_i) \
;         __builtin_amdgcn_global_load_lds((const unsigned*)((const char*)(gbase) + (RR)[_i] * (ld) + C2[_i]), (LAS unsigned*)(lds + (bufoff) + ldsw + _i * 8192), 16, 0, 0); } while (0)
; #define PG8_LDA(dst, b, h) do { _Pragma("unroll") for (int m = 0; m < 4; ++m) _Pragma("unroll") for (int k = 0; k < 2; ++k) dst[m][k] = *(const LAS bf16x8*)(lds + PG8_SA(b, h) + aoff + m * 2048 + k * 1024); } while (0)
; #define PG8_LDB(dst, b, h) do { _Pragma("unroll") for (int n = 0; n < 2; ++n) _Pragma("unroll") for (int k = 0; k < 2; ++k) dst[n][k] = *(const LAS bf16x8*)(lds + PG8_SB(b, h) + boff + n * 2048 + k * 1024); } while (0)
; #define PG8_MMA(ai, bj, At, Bt) do { __builtin_amdgcn_s_setprio(1); _Pragma("unroll") for (int m = 0; m < 4; ++m) _Pragma("unroll") for (int n = 0; n < 2; ++n) _Pragma("unroll") for (int k = 0; k < 2; ++k) \
;         acc[ai][bj][m][n] = __builtin_amdgcn_mfma_f32_16x16x32_bf16(Bt[n][k], At[m][k], acc[ai][bj][m][n], 0, 0, 0); __builtin_amdgcn_s_setprio(0); } while (0)
; #define PG8_WAIT_V(n) asm volatile("s_waitcnt vmcnt(" #n ")" ::: "memory")
; #define PG8_WAIT_L(n) asm volatile("s_waitcnt lgkmcnt(" #n ")" ::: "memory")
; #define PG8_BAR __builtin_amdgcn_s_barrier()
; #define PG8_SCHED __builtin_amdgcn_sched_barrier(0)
; template <class Sched, class Epi>
; __device__ __forceinline__ void gemm_run(LAS unsigned char* lds, const Sched& S, const Epi& E) {
;     ...
;             PG8_LDB(B0, 0, 0); PG8_LDB(B1, 0, 1); PG8_SCHED; PG8_LDA(At, 0, 0); PG8_STAGE(PG8_SA(1, 1), a1 + (size_t)HALF * lda, RA, lda);
;             PG8_WAIT_V(8); PG8_WAIT_L(0); PG8_BAR; PG8_MMA(0, 0, At, B0); PG8_MMA(0, 1, At, B1); PG8_BAR; PG8_SCHED;
;     ...
; #pragma unroll
;         for (int a = 0; a < 2; ++a)
; #pragma unroll
;             for (int b = 0; b < 2; ++b)
; #pragma unroll
;                 for (int m = 0; m < 4; ++m)
; #pragma unroll
;                     for (int n = 0; n < 2; ++n) acc[a][b][m][n] = (f32x4){0.f, 0.f, 0.f, 0.f};
;         cur = nxt; cA = nA; cB = nB; lda = nlda; ldb = nldb; ++ui;
.LBB0_1123:
	s_add_u32 s55, s30, 0x100
	v_mov_b32_e32 v2, 0
	s_addc_u32 s56, s31, 0
	s_mov_b32 s57, -2
	s_mov_b64 s[30:31], 0
	s_waitcnt lgkmcnt(0)
	v_mov_b32_e32 v3, v2
	v_mov_b32_e32 v4, v2
	v_mov_b32_e32 v5, v2
	v_mov_b32_e32 v6, v2
	v_mov_b32_e32 v7, v2
	v_mov_b32_e32 v8, v2
	v_mov_b32_e32 v9, v2
	v_mov_b32_e32 v18, v2
	v_mov_b32_e32 v19, v2
	v_mov_b32_e32 v20, v2
	v_mov_b32_e32 v21, v2
	v_mov_b32_e32 v22, v2
	v_mov_b32_e32 v23, v2
	v_mov_b32_e32 v24, v2
	v_mov_b32_e32 v25, v2
	v_mov_b32_e32 v34, v2
	v_mov_b32_e32 v35, v2
	v_mov_b32_e32 v36, v2
	v_mov_b32_e32 v37, v2
	v_mov_b32_e32 v38, v2
	v_mov_b32_e32 v39, v2
	v_mov_b32_e32 v40, v2
	v_mov_b32_e32 v41, v2
	v_mov_b32_e32 v50, v2
	v_mov_b32_e32 v51, v2
	v_mov_b32_e32 v52, v2
	v_mov_b32_e32 v53, v2
	v_mov_b32_e32 v54, v2
	v_mov_b32_e32 v55, v2
	v_mov_b32_e32 v56, v2
	v_mov_b32_e32 v57, v2
	v_mov_b32_e32 v10, v2
	v_mov_b32_e32 v11, v2
	v_mov_b32_e32 v12, v2
	v_mov_b32_e32 v13, v2
	v_mov_b32_e32 v14, v2
	v_mov_b32_e32 v15, v2
	v_mov_b32_e32 v16, v2
	v_mov_b32_e32 v17, v2
	v_mov_b32_e32 v26, v2
	v_mov_b32_e32 v27, v2
	v_mov_b32_e32 v28, v2
	v_mov_b32_e32 v29, v2
	v_mov_b32_e32 v30, v2
	v_mov_b32_e32 v31, v2
	v_mov_b32_e32 v32, v2
	v_mov_b32_e32 v33, v2
	v_mov_b32_e32 v42, v2
	v_mov_b32_e32 v43, v2
	v_mov_b32_e32 v44, v2
	v_mov_b32_e32 v45, v2
	v_mov_b32_e32 v46, v2
	v_mov_b32_e32 v47, v2
	v_mov_b32_e32 v48, v2
	v_mov_b32_e32 v49, v2
	v_mov_b32_e32 v58, v2
	v_mov_b32_e32 v59, v2
	v_mov_b32_e32 v60, v2
	v_mov_b32_e32 v61, v2
	v_mov_b32_e32 v62, v2
	v_mov_b32_e32 v63, v2
	v_mov_b32_e32 v64, v2
	v_mov_b32_e32 v65, v2
	v_mov_b32_e32 v66, v2
	v_mov_b32_e32 v67, v2
	v_mov_b32_e32 v68, v2
	v_mov_b32_e32 v69, v2
	v_mov_b32_e32 v70, v2
	v_mov_b32_e32 v71, v2
	v_mov_b32_e32 v72, v2
	v_mov_b32_e32 v73, v2
	v_mov_b32_e32 v82, v2
	v_mov_b32_e32 v83, v2
	v_mov_b32_e32 v84, v2
	v_mov_b32_e32 v85, v2
	v_mov_b32_e32 v86, v2
	v_mov_b32_e32 v87, v2
	v_mov_b32_e32 v88, v2
	v_mov_b32_e32 v89, v2
	v_mov_b32_e32 v98, v2
	v_mov_b32_e32 v99, v2
	v_mov_b32_e32 v100, v2
	v_mov_b32_e32 v101, v2
	v_mov_b32_e32 v102, v2
	v_mov_b32_e32 v103, v2
	v_mov_b32_e32 v104, v2
	v_mov_b32_e32 v105, v2
	v_mov_b32_e32 v114, v2
	v_mov_b32_e32 v115, v2
	v_mov_b32_e32 v116, v2
	v_mov_b32_e32 v117, v2
	v_mov_b32_e32 v118, v2
	v_mov_b32_e32 v119, v2
	v_mov_b32_e32 v120, v2
	v_mov_b32_e32 v121, v2
	v_mov_b32_e32 v74, v2
	v_mov_b32_e32 v75, v2
	v_mov_b32_e32 v76, v2
	v_mov_b32_e32 v77, v2
	v_mov_b32_e32 v78, v2
	v_mov_b32_e32 v79, v2
	v_mov_b32_e32 v80, v2
	v_mov_b32_e32 v81, v2
	v_mov_b32_e32 v90, v2
	v_mov_b32_e32 v91, v2
	v_mov_b32_e32 v92, v2
	v_mov_b32_e32 v93, v2
	v_mov_b32_e32 v94, v2
	v_mov_b32_e32 v95, v2
	v_mov_b32_e32 v96, v2
	v_mov_b32_e32 v97, v2
	v_mov_b32_e32 v106, v2
	v_mov_b32_e32 v107, v2
	v_mov_b32_e32 v108, v2
	v_mov_b32_e32 v109, v2
	v_mov_b32_e32 v110, v2
	v_mov_b32_e32 v111, v2
	v_mov_b32_e32 v112, v2
	v_mov_b32_e32 v113, v2
	v_mov_b32_e32 v122, v2
	v_mov_b32_e32 v123, v2
	v_mov_b32_e32 v124, v2
	v_mov_b32_e32 v125, v2
	v_mov_b32_e32 v126, v2
	v_mov_b32_e32 v127, v2
	v_mov_b32_e32 v128, v2
	v_mov_b32_e32 v129, v2
	.p2align 6
.LBB0_1124:
	ds_read_b128 v[154:157], v150
	ds_read_b128 v[158:161], v150 offset:1024
	ds_read_b128 v[162:165], v150 offset:2048
	ds_read_b128 v[166:169], v150 offset:3072
	ds_read_b128 v[170:173], v151
	ds_read_b128 v[174:177], v151 offset:1024
	ds_read_b128 v[178:181], v151 offset:2048
	ds_read_b128 v[182:185], v151 offset:3072
	s_add_u32 s36, s28, s30
	s_addc_u32 s37, s29, s31
	s_mov_b32 s98, s36
	s_mov_b32 s99, s37
	s_add_u32 s36, s36, 0x100
	s_addc_u32 s37, s37, 0
	s_add_u32 s58, s55, s30
	s_addc_u32 s59, s56, s31
	s_cmpk_eq_i32 s30, 0x2b00
	s_cselect_b32 s39, s19, s37
	s_cselect_b32 s38, s18, s36
	s_cselect_b32 s37, s23, s59
	s_cselect_b32 s36, s22, s58
	s_mov_b64 s[100:101], s[38:39]
	s_add_i32 m0, s33, 0xc000
	ds_read_b128 v[186:189], v152
	ds_read_b128 v[190:193], v152 offset:1024
	ds_read_b128 v[194:197], v152 offset:2048
	ds_read_b128 v[198:201], v152 offset:3072
	ds_read_b128 v[202:205], v152 offset:4096
	ds_read_b128 v[206:209], v152 offset:5120
	ds_read_b128 v[210:213], v152 offset:6144
	ds_read_b128 v[214:217], v152 offset:7168
	global_load_lds_dwordx4 v142, s[98:99]
	s_add_i32 m0, s33, 0xe000
	s_nop 0
	global_load_lds_dwordx4 v144, s[98:99]
	s_waitcnt vmcnt(8)
	s_waitcnt lgkmcnt(0)
	s_barrier
	s_waitcnt lgkmcnt(0)
	v_mfma_f32_16x16x32_bf16 v[126:129], v[154:157], v[186:189], v[126:129]
	v_mfma_f32_16x16x32_bf16 v[122:125], v[162:165], v[186:189], v[122:125]
	v_mfma_f32_16x16x32_bf16 v[110:113], v[154:157], v[194:197], v[110:113]
	v_mfma_f32_16x16x32_bf16 v[106:109], v[162:165], v[194:197], v[106:109]
	v_mfma_f32_16x16x32_bf16 v[94:97], v[154:157], v[202:205], v[94:97]
	v_mfma_f32_16x16x32_bf16 v[90:93], v[162:165], v[202:205], v[90:93]
	v_mfma_f32_16x16x32_bf16 v[78:81], v[154:157], v[210:213], v[78:81]
	v_mfma_f32_16x16x32_bf16 v[74:77], v[162:165], v[210:213], v[74:77]
	v_mfma_f32_16x16x32_bf16 v[126:129], v[158:161], v[190:193], v[126:129]
	v_mfma_f32_16x16x32_bf16 v[122:125], v[166:169], v[190:193], v[122:125]
	v_mfma_f32_16x16x32_bf16 v[110:113], v[158:161], v[198:201], v[110:113]
	v_mfma_f32_16x16x32_bf16 v[106:109], v[166:169], v[198:201], v[106:109]
	v_mfma_f32_16x16x32_bf16 v[94:97], v[158:161], v[206:209], v[94:97]
	v_mfma_f32_16x16x32_bf16 v[90:93], v[166:169], v[206:209], v[90:93]
	v_mfma_f32_16x16x32_bf16 v[78:81], v[158:161], v[214:217], v[78:81]
	v_mfma_f32_16x16x32_bf16 v[74:77], v[166:169], v[214:217], v[74:77]
	v_mfma_f32_16x16x32_bf16 v[118:121], v[170:173], v[186:189], v[118:121]
	v_mfma_f32_16x16x32_bf16 v[114:117], v[178:181], v[186:189], v[114:117]
	v_mfma_f32_16x16x32_bf16 v[102:105], v[170:173], v[194:197], v[102:105]
	v_mfma_f32_16x16x32_bf16 v[98:101], v[178:181], v[194:197], v[98:101]
	v_mfma_f32_16x16x32_bf16 v[86:89], v[170:173], v[202:205], v[86:89]
	v_mfma_f32_16x16x32_bf16 v[82:85], v[178:181], v[202:205], v[82:85]
	v_mfma_f32_16x16x32_bf16 v[70:73], v[170:173], v[210:213], v[70:73]
	v_mfma_f32_16x16x32_bf16 v[66:69], v[178:181], v[210:213], v[66:69]
	v_mfma_f32_16x16x32_bf16 v[118:121], v[174:177], v[190:193], v[118:121]
	v_mfma_f32_16x16x32_bf16 v[114:117], v[182:185], v[190:193], v[114:117]
	v_mfma_f32_16x16x32_bf16 v[102:105], v[174:177], v[198:201], v[102:105]
	v_mfma_f32_16x16x32_bf16 v[98:101], v[182:185], v[198:201], v[98:101]
	v_mfma_f32_16x16x32_bf16 v[86:89], v[174:177], v[206:209], v[86:89]
	v_mfma_f32_16x16x32_bf16 v[82:85], v[182:185], v[206:209], v[82:85]
	v_mfma_f32_16x16x32_bf16 v[70:73], v[174:177], v[214:217], v[70:73]
	v_mfma_f32_16x16x32_bf16 v[66:69], v[182:185], v[214:217], v[66:69]
	s_barrier
; #define PG8_STAGE(bufoff, gbase, RR, ld) do { _Pragma("unroll") for (int _i = 0; _i < 2; ++_i) \
;         __builtin_amdgcn_global_load_lds((const unsigned*)((const char*)(gbase) + (RR)[_i] * (ld) + C2[_i]), (LAS unsigned*)(lds + (bufoff) + ldsw + _i * 8192), 16, 0, 0); } while (0)
; #define PG8_LDA(dst, b, h) do { _Pragma("unroll") for (int m = 0; m < 4; ++m) _Pragma("unroll") for (int k = 0; k < 2; ++k) dst[m][k] = *(const LAS bf16x8*)(lds + PG8_SA(b, h) + aoff + m * 2048 + k * 1024); } while (0)
; #define PG8_LDB(dst, b, h) do { _Pragma("unroll") for (int n = 0; n < 2; ++n) _Pragma("unroll") for (int k = 0; k < 2; ++k) dst[n][k] = *(const LAS bf16x8*)(lds + PG8_SB(b, h) + boff + n * 2048 + k * 1024); } while (0)
; #define PG8_MMA(ai, bj, At, Bt) do { __builtin_amdgcn_s_setprio(1); _Pragma("unroll") for (int m = 0; m < 4; ++m) _Pragma("unroll") for (int n = 0; n < 2; ++n) _Pragma("unroll") for (int k = 0; k < 2; ++k) \
;         acc[ai][bj][m][n] = __builtin_amdgcn_mfma_f32_16x16x32_bf16(Bt[n][k], At[m][k], acc[ai][bj][m][n], 0, 0, 0); __builtin_amdgcn_s_setprio(0); } while (0)
; #define PG8_WAIT_V(n) asm volatile("s_waitcnt vmcnt(" #n ")" ::: "memory")
; #define PG8_WAIT_L(n) asm volatile("s_waitcnt lgkmcnt(" #n ")" ::: "memory")
; #define PG8_BAR __builtin_amdgcn_s_barrier()
; #define PG8_SCHED __builtin_amdgcn_sched_barrier(0)
; template <class Sched, class Epi>
; __device__ __forceinline__ void gemm_run(LAS unsigned char* lds, const Sched& S, const Epi& E) {
;     ...
;             PG8_LDA(At, 0, 1); PG8_STAGE(PG8_SB(0, 0), b2, RB, lb2); PG8_STAGE(PG8_SB(0, 1), b2 + (size_t)HALF * lb2, RB, lb2); PG8_STAGE(PG8_SA(0, 0), a2, RA, la2);
;             PG8_WAIT_V(8); PG8_WAIT_L(0); PG8_BAR; PG8_MMA(1, 0, At, B0); PG8_MMA(1, 1, At, B1); PG8_BAR; PG8_SCHED;
;             PG8_LDB(B0, 1, 0); PG8_LDB(B1, 1, 1); PG8_SCHED; PG8_LDA(At, 1, 0); PG8_STAGE(PG8_SA(0, 1), a2 + (size_t)HALF * la2, RA, la2);
;             PG8_WAIT_V(8); PG8_WAIT_L(0); PG8_BAR; PG8_MMA(0, 0, At, B0); PG8_MMA(0, 1, At, B1); PG8_BAR; PG8_SCHED;
	s_add_i32 s58, s49, s3
	s_mov_b32 m0, s58
	ds_read_b128 v[186:189], v152 offset:16384
	ds_read_b128 v[190:193], v152 offset:17408
	ds_read_b128 v[194:197], v152 offset:18432
	ds_read_b128 v[198:201], v152 offset:19456
	ds_read_b128 v[202:205], v152 offset:20480
	ds_read_b128 v[206:209], v152 offset:21504
	ds_read_b128 v[210:213], v152 offset:22528
	ds_read_b128 v[214:217], v152 offset:23552
	global_load_lds_dwordx4 v132, s[36:37]
	s_add_i32 m0, s58, 0x2000
	s_add_u32 s58, s36, 0x160000
	s_addc_u32 s59, s37, 0
	s_add_i32 s60, s50, s3
	global_load_lds_dwordx4 v134, s[36:37]
	s_mov_b32 m0, s60
	s_nop 0
	global_load_lds_dwordx4 v132, s[58:59]
	s_add_i32 m0, s60, 0x2000
	s_nop 0
	global_load_lds_dwordx4 v134, s[58:59]
	s_mov_b32 m0, s33
	s_nop 0
	global_load_lds_dwordx4 v136, s[38:39]
	s_mov_b32 m0, s35
	s_nop 0
	global_load_lds_dwordx4 v138, s[38:39]
	s_waitcnt vmcnt(8)
	s_waitcnt lgkmcnt(0)
	s_barrier
	s_waitcnt lgkmcnt(0)
	v_mfma_f32_16x16x32_bf16 v[62:65], v[154:157], v[186:189], v[62:65]
	v_mfma_f32_16x16x32_bf16 v[58:61], v[162:165], v[186:189], v[58:61]
	v_mfma_f32_16x16x32_bf16 v[46:49], v[154:157], v[194:197], v[46:49]
	v_mfma_f32_16x16x32_bf16 v[42:45], v[162:165], v[194:197], v[42:45]
	v_mfma_f32_16x16x32_bf16 v[30:33], v[154:157], v[202:205], v[30:33]
	v_mfma_f32_16x16x32_bf16 v[26:29], v[162:165], v[202:205], v[26:29]
	v_mfma_f32_16x16x32_bf16 v[14:17], v[154:157], v[210:213], v[14:17]
	v_mfma_f32_16x16x32_bf16 v[10:13], v[162:165], v[210:213], v[10:13]
	v_mfma_f32_16x16x32_bf16 v[62:65], v[158:161], v[190:193], v[62:65]
	v_mfma_f32_16x16x32_bf16 v[58:61], v[166:169], v[190:193], v[58:61]
	v_mfma_f32_16x16x32_bf16 v[46:49], v[158:161], v[198:201], v[46:49]
	v_mfma_f32_16x16x32_bf16 v[42:45], v[166:169], v[198:201], v[42:45]
	v_mfma_f32_16x16x32_bf16 v[30:33], v[158:161], v[206:209], v[30:33]
	v_mfma_f32_16x16x32_bf16 v[26:29], v[166:169], v[206:209], v[26:29]
	v_mfma_f32_16x16x32_bf16 v[14:17], v[158:161], v[214:217], v[14:17]
	v_mfma_f32_16x16x32_bf16 v[10:13], v[166:169], v[214:217], v[10:13]
	v_mfma_f32_16x16x32_bf16 v[54:57], v[170:173], v[186:189], v[54:57]
	v_mfma_f32_16x16x32_bf16 v[50:53], v[178:181], v[186:189], v[50:53]
	v_mfma_f32_16x16x32_bf16 v[38:41], v[170:173], v[194:197], v[38:41]
	v_mfma_f32_16x16x32_bf16 v[34:37], v[178:181], v[194:197], v[34:37]
	v_mfma_f32_16x16x32_bf16 v[22:25], v[170:173], v[202:205], v[22:25]
	v_mfma_f32_16x16x32_bf16 v[18:21], v[178:181], v[202:205], v[18:21]
	v_mfma_f32_16x16x32_bf16 v[6:9], v[170:173], v[210:213], v[6:9]
	v_mfma_f32_16x16x32_bf16 v[2:5], v[178:181], v[210:213], v[2:5]
	v_mfma_f32_16x16x32_bf16 v[54:57], v[174:177], v[190:193], v[54:57]
	v_mfma_f32_16x16x32_bf16 v[50:53], v[182:185], v[190:193], v[50:53]
	v_mfma_f32_16x16x32_bf16 v[38:41], v[174:177], v[198:201], v[38:41]
	v_mfma_f32_16x16x32_bf16 v[34:37], v[182:185], v[198:201], v[34:37]
	v_mfma_f32_16x16x32_bf16 v[22:25], v[174:177], v[206:209], v[22:25]
	v_mfma_f32_16x16x32_bf16 v[18:21], v[182:185], v[206:209], v[18:21]
	v_mfma_f32_16x16x32_bf16 v[6:9], v[174:177], v[214:217], v[6:9]
	v_mfma_f32_16x16x32_bf16 v[2:5], v[182:185], v[214:217], v[2:5]
	s_barrier
	s_add_i32 s58, 0, 0x18000
	s_add_i32 s59, 0, 0x1c000
	v_add_u32_e32 v166, s58, v141
	v_add_u32_e32 v182, s59, v141
	ds_read_b128 v[154:157], v166
	ds_read_b128 v[158:161], v166 offset:1024
	ds_read_b128 v[162:165], v166 offset:2048
	ds_read_b128 v[166:169], v166 offset:3072
	ds_read_b128 v[170:173], v182
	ds_read_b128 v[174:177], v182 offset:1024
	ds_read_b128 v[178:181], v182 offset:2048
	ds_read_b128 v[182:185], v182 offset:3072
	s_add_u32 s38, s38, 0x160000
	s_addc_u32 s39, s39, 0
	s_mov_b32 m0, s40
	ds_read_b128 v[186:189], v152 offset:32768
	ds_read_b128 v[190:193], v152 offset:33792
	ds_read_b128 v[194:197], v152 offset:34816
	ds_read_b128 v[198:201], v152 offset:35840
	ds_read_b128 v[202:205], v152 offset:36864
	ds_read_b128 v[206:209], v152 offset:37888
	ds_read_b128 v[210:213], v152 offset:38912
	ds_read_b128 v[214:217], v152 offset:39936
	global_load_lds_dwordx4 v136, s[38:39]
	s_mov_b32 m0, s41
	s_nop 0
	global_load_lds_dwordx4 v138, s[38:39]
	s_waitcnt vmcnt(8)
	s_waitcnt lgkmcnt(0)
	s_barrier
; #define PG8_STAGE(bufoff, gbase, RR, ld) do { _Pragma("unroll") for (int _i = 0; _i < 2; ++_i) \
;         __builtin_amdgcn_global_load_lds((const unsigned*)((const char*)(gbase) + (RR)[_i] * (ld) + C2[_i]), (LAS unsigned*)(lds + (bufoff) + ldsw + _i * 8192), 16, 0, 0); } while (0)
; #define PG8_LDA(dst, b, h) do { _Pragma("unroll") for (int m = 0; m < 4; ++m) _Pragma("unroll") for (int k = 0; k < 2; ++k) dst[m][k] = *(const LAS bf16x8*)(lds + PG8_SA(b, h) + aoff + m * 2048 + k * 1024); } while (0)
; #define PG8_MMA(ai, bj, At, Bt) do { __builtin_amdgcn_s_setprio(1); _Pragma("unroll") for (int m = 0; m < 4; ++m) _Pragma("unroll") for (int n = 0; n < 2; ++n) _Pragma("unroll") for (int k = 0; k < 2; ++k) \
;         acc[ai][bj][m][n] = __builtin_amdgcn_mfma_f32_16x16x32_bf16(Bt[n][k], At[m][k], acc[ai][bj][m][n], 0, 0, 0); __builtin_amdgcn_s_setprio(0); } while (0)
; #define PG8_WAIT_V(n) asm volatile("s_waitcnt vmcnt(" #n ")" ::: "memory")
; #define PG8_WAIT_L(n) asm volatile("s_waitcnt lgkmcnt(" #n ")" ::: "memory")
; #define PG8_BAR __builtin_amdgcn_s_barrier()
; #define PG8_SCHED __builtin_amdgcn_sched_barrier(0)
; template <class Sched, class Epi>
; __device__ __forceinline__ void gemm_run(LAS unsigned char* lds, const Sched& S, const Epi& E) {
;     ...
;             PG8_LDA(At, 1, 1); PG8_STAGE(PG8_SB(1, 0), b3, RB, lb2); PG8_STAGE(PG8_SB(1, 1), b3 + (size_t)HALF * lb2, RB, lb2); PG8_STAGE(PG8_SA(1, 0), a3, RA, la2);
;             PG8_WAIT_V(8); PG8_WAIT_L(0); PG8_BAR; PG8_MMA(1, 0, At, B0); PG8_MMA(1, 1, At, B1); PG8_BAR; PG8_SCHED;
;         }
	s_waitcnt lgkmcnt(0)
	v_mfma_f32_16x16x32_bf16 v[126:129], v[154:157], v[186:189], v[126:129]
	v_mfma_f32_16x16x32_bf16 v[122:125], v[162:165], v[186:189], v[122:125]
	v_mfma_f32_16x16x32_bf16 v[110:113], v[154:157], v[194:197], v[110:113]
	v_mfma_f32_16x16x32_bf16 v[106:109], v[162:165], v[194:197], v[106:109]
	v_mfma_f32_16x16x32_bf16 v[94:97], v[154:157], v[202:205], v[94:97]
	v_mfma_f32_16x16x32_bf16 v[90:93], v[162:165], v[202:205], v[90:93]
	v_mfma_f32_16x16x32_bf16 v[78:81], v[154:157], v[210:213], v[78:81]
	v_mfma_f32_16x16x32_bf16 v[74:77], v[162:165], v[210:213], v[74:77]
	v_mfma_f32_16x16x32_bf16 v[126:129], v[158:161], v[190:193], v[126:129]
	v_mfma_f32_16x16x32_bf16 v[122:125], v[166:169], v[190:193], v[122:125]
	v_mfma_f32_16x16x32_bf16 v[110:113], v[158:161], v[198:201], v[110:113]
	v_mfma_f32_16x16x32_bf16 v[106:109], v[166:169], v[198:201], v[106:109]
	v_mfma_f32_16x16x32_bf16 v[94:97], v[158:161], v[206:209], v[94:97]
	v_mfma_f32_16x16x32_bf16 v[90:93], v[166:169], v[206:209], v[90:93]
	v_mfma_f32_16x16x32_bf16 v[78:81], v[158:161], v[214:217], v[78:81]
	v_mfma_f32_16x16x32_bf16 v[74:77], v[166:169], v[214:217], v[74:77]
	v_mfma_f32_16x16x32_bf16 v[118:121], v[170:173], v[186:189], v[118:121]
	v_mfma_f32_16x16x32_bf16 v[114:117], v[178:181], v[186:189], v[114:117]
	v_mfma_f32_16x16x32_bf16 v[102:105], v[170:173], v[194:197], v[102:105]
	v_mfma_f32_16x16x32_bf16 v[98:101], v[178:181], v[194:197], v[98:101]
	v_mfma_f32_16x16x32_bf16 v[86:89], v[170:173], v[202:205], v[86:89]
	v_mfma_f32_16x16x32_bf16 v[82:85], v[178:181], v[202:205], v[82:85]
	v_mfma_f32_16x16x32_bf16 v[70:73], v[170:173], v[210:213], v[70:73]
	v_mfma_f32_16x16x32_bf16 v[66:69], v[178:181], v[210:213], v[66:69]
	v_mfma_f32_16x16x32_bf16 v[118:121], v[174:177], v[190:193], v[118:121]
	v_mfma_f32_16x16x32_bf16 v[114:117], v[182:185], v[190:193], v[114:117]
	v_mfma_f32_16x16x32_bf16 v[102:105], v[174:177], v[198:201], v[102:105]
	v_mfma_f32_16x16x32_bf16 v[98:101], v[182:185], v[198:201], v[98:101]
	v_mfma_f32_16x16x32_bf16 v[86:89], v[174:177], v[206:209], v[86:89]
	v_mfma_f32_16x16x32_bf16 v[82:85], v[182:185], v[206:209], v[82:85]
	v_mfma_f32_16x16x32_bf16 v[70:73], v[174:177], v[214:217], v[70:73]
	v_mfma_f32_16x16x32_bf16 v[66:69], v[182:185], v[214:217], v[66:69]
	s_barrier
	s_add_i32 s38, s58, s3
	s_mov_b32 m0, s38
	ds_read_b128 v[186:189], v152 offset:49152
	ds_read_b128 v[190:193], v152 offset:50176
	ds_read_b128 v[194:197], v152 offset:51200
	ds_read_b128 v[198:201], v152 offset:52224
	ds_read_b128 v[202:205], v152 offset:53248
	ds_read_b128 v[206:209], v152 offset:54272
	ds_read_b128 v[210:213], v152 offset:55296
	ds_read_b128 v[214:217], v152 offset:56320
	s_add_u32 s98, s36, 0x80
	s_addc_u32 s99, s37, 0
	global_load_lds_dwordx4 v132, s[98:99]
	s_add_i32 m0, s38, 0x2000
	s_nop 0
	global_load_lds_dwordx4 v134, s[98:99]
	s_add_u32 s36, s36, 0x160080
	s_addc_u32 s37, s37, 0
	s_add_i32 s38, s59, s3
	s_mov_b32 m0, s38
	s_nop 0
	global_load_lds_dwordx4 v132, s[36:37]
	s_add_i32 m0, s38, 0x2000
	s_nop 0
	global_load_lds_dwordx4 v134, s[36:37]
	s_mov_b32 m0, s43
	s_nop 0
	s_add_u32 s100, s100, 0x80
	s_addc_u32 s101, s101, 0
	global_load_lds_dwordx4 v136, s[100:101]
	s_mov_b32 m0, s44
	s_nop 0
	global_load_lds_dwordx4 v138, s[100:101]
	s_waitcnt vmcnt(8)
	s_waitcnt lgkmcnt(0)
	s_barrier
	s_waitcnt lgkmcnt(0)
	v_mfma_f32_16x16x32_bf16 v[62:65], v[154:157], v[186:189], v[62:65]
	v_mfma_f32_16x16x32_bf16 v[58:61], v[162:165], v[186:189], v[58:61]
	v_mfma_f32_16x16x32_bf16 v[46:49], v[154:157], v[194:197], v[46:49]
	v_mfma_f32_16x16x32_bf16 v[42:45], v[162:165], v[194:197], v[42:45]
	v_mfma_f32_16x16x32_bf16 v[30:33], v[154:157], v[202:205], v[30:33]
	v_mfma_f32_16x16x32_bf16 v[26:29], v[162:165], v[202:205], v[26:29]
	v_mfma_f32_16x16x32_bf16 v[14:17], v[154:157], v[210:213], v[14:17]
	v_mfma_f32_16x16x32_bf16 v[10:13], v[162:165], v[210:213], v[10:13]
	v_mfma_f32_16x16x32_bf16 v[62:65], v[158:161], v[190:193], v[62:65]
	v_mfma_f32_16x16x32_bf16 v[58:61], v[166:169], v[190:193], v[58:61]
	v_mfma_f32_16x16x32_bf16 v[46:49], v[158:161], v[198:201], v[46:49]
	v_mfma_f32_16x16x32_bf16 v[42:45], v[166:169], v[198:201], v[42:45]
	v_mfma_f32_16x16x32_bf16 v[30:33], v[158:161], v[206:209], v[30:33]
	v_mfma_f32_16x16x32_bf16 v[26:29], v[166:169], v[206:209], v[26:29]
	v_mfma_f32_16x16x32_bf16 v[14:17], v[158:161], v[214:217], v[14:17]
	v_mfma_f32_16x16x32_bf16 v[10:13], v[166:169], v[214:217], v[10:13]
	v_mfma_f32_16x16x32_bf16 v[54:57], v[170:173], v[186:189], v[54:57]
	v_mfma_f32_16x16x32_bf16 v[50:53], v[178:181], v[186:189], v[50:53]
	v_mfma_f32_16x16x32_bf16 v[38:41], v[170:173], v[194:197], v[38:41]
	v_mfma_f32_16x16x32_bf16 v[34:37], v[178:181], v[194:197], v[34:37]
	v_mfma_f32_16x16x32_bf16 v[22:25], v[170:173], v[202:205], v[22:25]
	v_mfma_f32_16x16x32_bf16 v[18:21], v[178:181], v[202:205], v[18:21]
	v_mfma_f32_16x16x32_bf16 v[6:9], v[170:173], v[210:213], v[6:9]
	v_mfma_f32_16x16x32_bf16 v[2:5], v[178:181], v[210:213], v[2:5]
	v_mfma_f32_16x16x32_bf16 v[54:57], v[174:177], v[190:193], v[54:57]
	v_mfma_f32_16x16x32_bf16 v[50:53], v[182:185], v[190:193], v[50:53]
	v_mfma_f32_16x16x32_bf16 v[38:41], v[174:177], v[198:201], v[38:41]
	v_mfma_f32_16x16x32_bf16 v[34:37], v[182:185], v[198:201], v[34:37]
	v_mfma_f32_16x16x32_bf16 v[22:25], v[174:177], v[206:209], v[22:25]
	v_mfma_f32_16x16x32_bf16 v[18:21], v[182:185], v[206:209], v[18:21]
	v_mfma_f32_16x16x32_bf16 v[6:9], v[174:177], v[214:217], v[6:9]
	v_mfma_f32_16x16x32_bf16 v[2:5], v[182:185], v[214:217], v[2:5]
	s_barrier
	s_add_i32 s57, s57, 2
	s_add_u32 s30, s30, 0x100
	s_addc_u32 s31, s31, 0
	s_cmpk_gt_u32 s57, 0x55
	s_cbranch_scc0 .LBB0_1124
	s_and_b64 vcc, exec, s[12:13]
	s_cbranch_vccz .LBB0_1127
	s_barrier
